# GEMM LDS-DMA issue interleaved with post-barrier MFMAs (BN256 + MLP2), DPP/permlane wave sums, batched NA rpb loads
# speedup vs baseline: 1.0303x; 1.0303x over previous
.LBB0_89:
	s_or_b64 exec, exec, s[0:1]
	v_lshlrev_b32_e32 v31, 3, v29
	v_and_b32_e32 v30, 0x1f8, v31
	v_lshlrev_b32_e32 v16, 2, v30
	v_lshl_add_u64 v[2:3], v[2:3], 2, s[18:19]
	v_lshl_add_u64 v[4:5], v[0:1], 0, v[16:17]
	v_lshl_add_u64 v[22:23], v[2:3], 0, v[16:17]
	global_load_dwordx4 v[8:11], v[4:5], off offset:16
	global_load_dwordx4 v[12:15], v[4:5], off
	global_load_dwordx4 v[0:3], v[4:5], off offset:2064
	s_nop 0
	global_load_dwordx4 v[4:7], v[4:5], off offset:2048
	v_lshl_add_u64 v[24:25], s[28:29], 0, v[20:21]
	s_mov_b64 s[0:1], 0x1000
	s_add_i32 s8, s8, 1
	s_cmp_lg_u32 s8, 4
	s_waitcnt vmcnt(2)
	global_store_dwordx4 v[22:23], v[12:15], off
	global_store_dwordx4 v[22:23], v[8:11], off offset:16
	s_waitcnt vmcnt(2)
	global_store_dwordx4 v[22:23], v[4:7], off offset:2048
	global_store_dwordx4 v[22:23], v[0:3], off offset:2064
	v_pk_mul_f32 v[20:21], v[12:13], v[12:13]
	v_pk_mul_f32 v[22:23], v[14:15], v[14:15]
	v_add_f32_e32 v20, v20, v21
	v_add_f32_e32 v20, v20, v22
	v_pk_mul_f32 v[32:33], v[8:9], v[8:9]
	v_add_f32_e32 v20, v20, v23
	v_add_f32_e32 v20, v20, v32
	v_pk_mul_f32 v[34:35], v[10:11], v[10:11]
	v_add_f32_e32 v20, v20, v33
	v_add_f32_e32 v20, v20, v34
	v_pk_mul_f32 v[36:37], v[4:5], v[4:5]
	v_add_f32_e32 v20, v20, v35
	v_add_f32_e32 v20, v20, v36
	v_pk_mul_f32 v[38:39], v[6:7], v[6:7]
	v_add_f32_e32 v20, v20, v37
	v_add_f32_e32 v20, v20, v38
	v_pk_mul_f32 v[40:41], v[0:1], v[0:1]
	v_add_f32_e32 v20, v20, v39
	v_add_f32_e32 v20, v20, v40
	v_pk_mul_f32 v[42:43], v[2:3], v[2:3]
	v_add_f32_e32 v20, v20, v41
	v_lshl_add_u64 v[22:23], v[24:25], 0, s[0:1]
	v_add_f32_e32 v20, v20, v42
	v_lshl_add_u64 v[44:45], v[22:23], 0, v[16:17]
	v_add_f32_e32 v20, v20, v43
	v_lshl_add_u64 v[24:25], v[24:25], 0, v[16:17]
	global_load_dwordx4 v[32:35], v16, s[64:65] offset:16
	global_load_dwordx4 v[36:39], v16, s[64:65]
	global_load_dwordx4 v[40:43], v[44:45], off offset:16
	s_nop 0
	global_load_dwordx4 v[44:47], v[44:45], off
	s_nop 0
	global_load_dwordx4 v[48:51], v[24:25], off offset:16
	global_load_dwordx4 v[52:55], v[24:25], off
	s_mov_b32 s0, 0x800000
	s_waitcnt lgkmcnt(0)
	s_nop 1
	v_add_f32_dpp v20, v20, v20 quad_perm:[1,0,3,2] row_mask:0xf bank_mask:0xf
	s_nop 1
	v_add_f32_dpp v20, v20, v20 quad_perm:[2,3,0,1] row_mask:0xf bank_mask:0xf
	s_nop 1
	v_add_f32_dpp v20, v20, v20 row_half_mirror row_mask:0xf bank_mask:0xf
	s_nop 1
	v_add_f32_dpp v20, v20, v20 row_mirror row_mask:0xf bank_mask:0xf
	v_mov_b32_e32 v21, v20
	s_nop 1
	v_permlane16_swap_b32_e32 v20, v21
	v_add_f32_e32 v20, v20, v21
	v_mov_b32_e32 v21, v20
	s_nop 1
	v_permlane32_swap_b32_e32 v20, v21
	v_add_f32_e32 v20, v20, v21
	v_fmamk_f32 v20, v20, 0x3a800000, v27
	v_cmp_gt_f32_e64 s[0:1], s0, v20
	v_mul_f32_e32 v21, 0x4b800000, v20
	s_nop 0
	v_cndmask_b32_e64 v20, v20, v21, s[0:1]
	v_rsq_f32_e32 v20, v20
	s_nop 0
	v_mul_f32_e32 v21, 0x45800000, v20
	v_cndmask_b32_e64 v20, v20, v21, s[0:1]
	v_pk_mul_f32 v[12:13], v[12:13], v[20:21] op_sel_hi:[1,0]
	v_pk_mul_f32 v[14:15], v[14:15], v[20:21] op_sel_hi:[1,0]
	v_pk_mul_f32 v[8:9], v[8:9], v[20:21] op_sel_hi:[1,0]
	s_waitcnt vmcnt(4)
	v_pk_mul_f32 v[12:13], v[36:37], v[12:13]
	s_waitcnt vmcnt(2)
	v_pk_add_f32 v[36:37], v[44:45], 1.0 op_sel_hi:[1,0]
	v_pk_mul_f32 v[14:15], v[38:39], v[14:15]
	s_waitcnt vmcnt(0)
	v_pk_fma_f32 v[12:13], v[36:37], v[12:13], v[52:53]
	v_pk_add_f32 v[36:37], v[46:47], 1.0 op_sel_hi:[1,0]
	v_cvt_pk_bf16_f32 v12, v12, v13
	v_pk_fma_f32 v[14:15], v[36:37], v[14:15], v[54:55]
	v_pk_mul_f32 v[8:9], v[8:9], v[32:33]
	v_cvt_pk_bf16_f32 v13, v14, v15
	v_pk_add_f32 v[14:15], v[40:41], 1.0 op_sel_hi:[1,0]
	s_nop 0
	v_pk_fma_f32 v[8:9], v[8:9], v[14:15], v[48:49]
	s_nop 0
	v_cvt_pk_bf16_f32 v14, v8, v9
	v_pk_mul_f32 v[8:9], v[10:11], v[20:21] op_sel_hi:[1,0]
	v_pk_add_f32 v[10:11], v[42:43], 1.0 op_sel_hi:[1,0]
	v_pk_mul_f32 v[8:9], v[8:9], v[34:35]
	v_or_b32_e32 v21, 0x200, v30
	v_pk_fma_f32 v[8:9], v[8:9], v[10:11], v[50:51]
	v_pk_mul_f32 v[4:5], v[4:5], v[20:21] op_sel_hi:[1,0]
	v_cvt_pk_bf16_f32 v15, v8, v9
	v_bfe_u32 v8, v31, 5, 4
	v_mul_u32_u24_e32 v8, 0x9000, v8
	v_mov_b32_e32 v9, v17
	v_lshl_add_u64 v[8:9], v[8:9], 0, v[18:19]
	v_lshlrev_b64 v[8:9], 6, v[8:9]
	v_lshl_add_u64 v[10:11], s[4:5], 0, v[8:9]
	v_lshlrev_b32_e32 v8, 4, v29
	v_and_b32_e32 v8, 48, v8
	v_mov_b32_e32 v9, v17
	v_lshl_add_u64 v[10:11], v[10:11], 0, v[8:9]
	global_store_dwordx4 v[10:11], v[12:15], off
	v_lshlrev_b32_e32 v10, 2, v21
	v_mov_b32_e32 v11, v17
	v_lshl_add_u64 v[14:15], v[22:23], 0, v[10:11]
	global_load_dwordx4 v[10:13], v16, s[64:65] offset:2064
	global_load_dwordx4 v[30:33], v16, s[64:65] offset:2048
	global_load_dwordx4 v[34:37], v[14:15], off offset:16
	global_load_dwordx4 v[38:41], v[14:15], off
	global_load_dwordx4 v[42:45], v[24:25], off offset:2064
	s_nop 0
	global_load_dwordx4 v[22:25], v[24:25], off offset:2048
	v_pk_mul_f32 v[6:7], v[6:7], v[20:21] op_sel_hi:[1,0]
	v_pk_mul_f32 v[0:1], v[0:1], v[20:21] op_sel_hi:[1,0]
	s_waitcnt vmcnt(4)
	v_pk_mul_f32 v[4:5], v[4:5], v[30:31]
	s_waitcnt vmcnt(2)
	v_pk_add_f32 v[14:15], v[38:39], 1.0 op_sel_hi:[1,0]
	v_pk_mul_f32 v[6:7], v[6:7], v[32:33]
	s_waitcnt vmcnt(0)
	v_pk_fma_f32 v[4:5], v[4:5], v[14:15], v[22:23]
	v_pk_add_f32 v[14:15], v[40:41], 1.0 op_sel_hi:[1,0]
	v_cvt_pk_bf16_f32 v4, v4, v5
	v_pk_fma_f32 v[6:7], v[6:7], v[14:15], v[24:25]
	v_pk_mul_f32 v[0:1], v[0:1], v[10:11]
	v_cvt_pk_bf16_f32 v5, v6, v7
	v_pk_add_f32 v[6:7], v[34:35], 1.0 op_sel_hi:[1,0]
	s_nop 0
	v_pk_fma_f32 v[0:1], v[0:1], v[6:7], v[42:43]
	s_nop 0
	v_cvt_pk_bf16_f32 v6, v0, v1
	v_pk_mul_f32 v[0:1], v[2:3], v[20:21] op_sel_hi:[1,0]
	v_pk_add_f32 v[2:3], v[36:37], 1.0 op_sel_hi:[1,0]
	v_pk_mul_f32 v[0:1], v[0:1], v[12:13]
	s_nop 0
	v_pk_fma_f32 v[0:1], v[0:1], v[2:3], v[44:45]
	s_nop 0
	v_cvt_pk_bf16_f32 v7, v0, v1
	v_lshrrev_b32_e32 v0, 5, v21
	v_mul_u32_u24_e32 v16, 0x9000, v0
	v_lshl_add_u64 v[0:1], v[16:17], 0, v[18:19]
	v_lshlrev_b64 v[0:1], 6, v[0:1]
	v_lshl_add_u64 v[0:1], s[4:5], 0, v[0:1]
	v_lshl_add_u64 v[0:1], v[0:1], 0, v[8:9]
	global_store_dwordx4 v[0:1], v[4:7], off
	s_cbranch_scc0 .LBB0_82

.LBB0_124:
	s_or_b64 exec, exec, s[10:11]
	s_waitcnt lgkmcnt(0)
	s_barrier
	ds_read_b32 v0, v230
	s_waitcnt lgkmcnt(0)
	v_cmp_gt_i32_e32 vcc, 0, v0
	v_readfirstlane_b32 s10, v0
	s_cbranch_vccnz .LBB0_147
	s_and_b32 s34, s10, 63
	s_lshl_b32 s10, s10, 2
	s_and_b32 s25, s10, 0x7fffff00
	s_cmp_eq_u32 s34, 63
	s_mov_b64 s[10:11], -1
	s_cbranch_scc1 .LBB0_149
	v_mov_b32_e32 v203, v195
	s_movk_i32 s10, 0x78
	v_lshrrev_b32_e32 v1, 1, v203
	v_and_b32_e32 v1, 6, v1
	v_bfe_u32 v201, v203, 4, 2
	v_lshrrev_b32_e64 v1, v1, s10
	v_bitop3_b32 v1, v1, v201, 3 bitop3:0x6c
	v_lshlrev_b32_e32 v0, 1, v201
	v_lshlrev_b32_e32 v10, 4, v1
	v_ashrrev_i32_e32 v1, 1, v203
	v_ashrrev_i32_e32 v8, 6, v203
	v_lshrrev_b32_e64 v22, v0, s10
	v_and_b32_e32 v238, 15, v203
	v_and_b32_e32 v239, 0xffffff80, v1
	v_xor_b32_e32 v0, v22, v203
	v_bfe_u32 v24, v203, 2, 4
	v_or_b32_e32 v1, v239, v238
	v_lshlrev_b32_e32 v18, 4, v8
	v_lshl_or_b32 v240, v1, 6, v10
	v_lshlrev_b32_e32 v1, 6, v203
	v_lshlrev_b32_e32 v0, 4, v0
	v_ashrrev_i32_e32 v19, 31, v18
	v_or_b32_e32 v4, s25, v24
	v_mov_b32_e32 v5, v17
	v_and_b32_e32 v11, 0x33c0, v1
	v_and_b32_e32 v0, 48, v0
	v_mov_b32_e32 v1, v17
	v_lshl_add_u64 v[6:7], v[4:5], 0, v[18:19]
	v_lshlrev_b32_e32 v241, 10, v8
	v_lshl_add_u64 v[2:3], s[4:5], 0, v[0:1]
	v_lshlrev_b64 v[6:7], 6, v[6:7]
	v_readfirstlane_b32 s10, v241
	v_lshl_add_u64 v[6:7], v[2:3], 0, v[6:7]
	s_mov_b32 m0, s10
	v_add_u32_e32 v8, 8, v8
	global_load_lds_dwordx4 v[6:7], off
	v_lshlrev_b32_e32 v6, 4, v8
	v_ashrrev_i32_e32 v7, 31, v6
	v_lshl_add_u64 v[4:5], v[4:5], 0, v[6:7]
	v_lshlrev_b32_e32 v242, 10, v8
	s_lshl_b32 s34, s34, 8
	v_lshlrev_b64 v[4:5], 6, v[4:5]
	v_readfirstlane_b32 s10, v242
	v_readlane_b32 s40, v252, 19
	v_lshl_add_u64 v[4:5], v[2:3], 0, v[4:5]
	s_mov_b32 m0, s10
	v_or_b32_e32 v20, s34, v24
	v_mov_b32_e32 v21, v17
	v_readlane_b32 s41, v252, 20
	global_load_lds_dwordx4 v[4:5], off
	v_lshl_add_u64 v[4:5], v[20:21], 0, v[18:19]
	v_add_u32_e32 v8, 0x4000, v241
	v_lshl_add_u64 v[0:1], s[40:41], 0, v[0:1]
	v_lshlrev_b64 v[4:5], 6, v[4:5]
	v_readfirstlane_b32 s10, v8
	v_lshl_add_u64 v[4:5], v[0:1], 0, v[4:5]
	s_mov_b32 m0, s10
	v_add_u32_e32 v8, 0x4000, v242
	global_load_lds_dwordx4 v[4:5], off
	v_lshl_add_u64 v[4:5], v[20:21], 0, v[6:7]
	v_lshlrev_b64 v[4:5], 6, v[4:5]
	v_readfirstlane_b32 s10, v8
	v_lshl_add_u64 v[4:5], v[0:1], 0, v[4:5]
	s_mov_b32 m0, s10
	s_add_i32 s10, s25, 0x9000
	global_load_lds_dwordx4 v[4:5], off
	v_or_b32_e32 v4, s10, v24
	v_mov_b32_e32 v5, v17
	v_lshl_add_u64 v[8:9], v[4:5], 0, v[18:19]
	v_add_u32_e32 v12, 0x8000, v241
	v_lshlrev_b64 v[8:9], 6, v[8:9]
	v_readfirstlane_b32 s10, v12
	v_lshl_add_u64 v[8:9], v[2:3], 0, v[8:9]
	s_mov_b32 m0, s10
	v_lshl_add_u64 v[4:5], v[4:5], 0, v[6:7]
	global_load_lds_dwordx4 v[8:9], off
	v_add_u32_e32 v8, 0x8000, v242
	v_lshlrev_b64 v[4:5], 6, v[4:5]
	v_readfirstlane_b32 s10, v8
	v_lshl_add_u64 v[4:5], v[2:3], 0, v[4:5]
	s_mov_b32 m0, s10
	s_add_i32 s10, s34, 0xc80
	global_load_lds_dwordx4 v[4:5], off
	v_or_b32_e32 v4, s10, v24
	v_mov_b32_e32 v5, v17
	v_lshl_add_u64 v[8:9], v[4:5], 0, v[18:19]
	v_add_u32_e32 v12, 0xc000, v241
	v_lshlrev_b64 v[8:9], 6, v[8:9]
	v_readfirstlane_b32 s10, v12
	v_lshl_add_u64 v[8:9], v[0:1], 0, v[8:9]
	s_mov_b32 m0, s10
	v_lshl_add_u64 v[4:5], v[4:5], 0, v[6:7]
	global_load_lds_dwordx4 v[8:9], off
	v_add_u32_e32 v8, 0xc000, v242
	v_lshlrev_b64 v[4:5], 6, v[4:5]
	v_readfirstlane_b32 s10, v8
	v_lshl_add_u64 v[4:5], v[0:1], 0, v[4:5]
	s_mov_b32 m0, s10
	s_add_i32 s10, s25, 0x12000
	global_load_lds_dwordx4 v[4:5], off
	v_or_b32_e32 v4, s10, v24
	v_mov_b32_e32 v5, v17
	v_lshl_add_u64 v[8:9], v[4:5], 0, v[18:19]
	v_add_u32_e32 v12, 0x10000, v241
	v_lshlrev_b64 v[8:9], 6, v[8:9]
	v_readfirstlane_b32 s10, v12
	v_lshl_add_u64 v[8:9], v[2:3], 0, v[8:9]
	s_mov_b32 m0, s10
	v_lshl_add_u64 v[4:5], v[4:5], 0, v[6:7]
	global_load_lds_dwordx4 v[8:9], off
	v_add_u32_e32 v8, 0x10000, v242
	v_lshlrev_b64 v[4:5], 6, v[4:5]
	v_readfirstlane_b32 s10, v8
	v_lshl_add_u64 v[4:5], v[2:3], 0, v[4:5]
	s_mov_b32 m0, s10
	s_add_i32 s10, s34, 0x1900
	global_load_lds_dwordx4 v[4:5], off
	v_or_b32_e32 v4, s10, v24
	v_mov_b32_e32 v5, v17
	v_lshl_add_u64 v[8:9], v[4:5], 0, v[18:19]
	v_add_u32_e32 v12, 0x14000, v241
	v_lshlrev_b64 v[8:9], 6, v[8:9]
	v_readfirstlane_b32 s10, v12
	v_lshl_add_u64 v[8:9], v[0:1], 0, v[8:9]
	s_mov_b32 m0, s10
	v_lshl_add_u64 v[4:5], v[4:5], 0, v[6:7]
	global_load_lds_dwordx4 v[8:9], off
	v_add_u32_e32 v8, 0x14000, v242
	v_lshlrev_b64 v[4:5], 6, v[4:5]
	v_readfirstlane_b32 s10, v8
	v_lshl_add_u64 v[4:5], v[0:1], 0, v[4:5]
	s_mov_b32 m0, s10
	s_add_i32 s10, s25, 0x1b000
	global_load_lds_dwordx4 v[4:5], off
	v_or_b32_e32 v4, s10, v24
	v_mov_b32_e32 v5, v17
	v_lshl_add_u64 v[8:9], v[4:5], 0, v[18:19]
	v_lshl_add_u64 v[4:5], v[4:5], 0, v[6:7]
	v_lshlrev_b64 v[8:9], 6, v[8:9]
	v_add_u32_e32 v12, 0x18000, v241
	v_lshlrev_b64 v[4:5], 6, v[4:5]
	v_lshl_add_u64 v[8:9], v[2:3], 0, v[8:9]
	v_readfirstlane_b32 s10, v12
	v_lshl_add_u64 v[2:3], v[2:3], 0, v[4:5]
	v_add_u32_e32 v4, 0x18000, v242
	s_mov_b32 m0, s10
	v_readfirstlane_b32 s10, v4
	global_load_lds_dwordx4 v[8:9], off
	s_mov_b32 m0, s10
	s_add_i32 s10, s34, 0x2580
	global_load_lds_dwordx4 v[2:3], off
	v_or_b32_e32 v2, s10, v24
	v_mov_b32_e32 v3, v17
	v_lshl_add_u64 v[4:5], v[2:3], 0, v[18:19]
	v_lshl_add_u64 v[2:3], v[2:3], 0, v[6:7]
	v_lshlrev_b64 v[4:5], 6, v[4:5]
	v_add_u32_e32 v8, 0x1c000, v241
	v_lshlrev_b64 v[2:3], 6, v[2:3]
	v_lshl_add_u64 v[4:5], v[0:1], 0, v[4:5]
	v_readfirstlane_b32 s10, v8
	v_lshl_add_u64 v[0:1], v[0:1], 0, v[2:3]
	v_add_u32_e32 v2, 0x1c000, v242
	s_mov_b32 m0, s10
	v_readfirstlane_b32 s10, v2
	global_load_lds_dwordx4 v[4:5], off
	s_mov_b32 m0, s10
	s_movk_i32 s10, 0x4000
	global_load_lds_dwordx4 v[0:1], off
	v_or3_b32 v243, v11, v10, s10
	s_waitcnt vmcnt(12)
	s_barrier
	ds_read_b128 v[0:3], v243 offset:0
	ds_read_b128 v[4:7], v243 offset:1024
	ds_read_b128 v[8:11], v243 offset:2048
	ds_read_b128 v[12:15], v243 offset:3072
	v_bitop3_b32 v21, v22, 3, v203 bitop3:0x48
	ds_read_b128 v[58:61], v240 offset:0
	v_lshlrev_b32_e32 v206, 4, v21
	v_add_u32_e32 v22, 0x3e80, v20
	v_mov_b32_e32 v23, v17
	v_add_u32_e32 v20, 0x3200, v20
	v_mov_b32_e32 v21, v17
	ds_read_b128 v[54:57], v240 offset:1024
	v_lshl_add_u64 v[22:23], v[18:19], 0, v[22:23]
	v_lshl_add_u64 v[20:21], v[18:19], 0, v[20:21]
	ds_read_b128 v[50:53], v240 offset:2048
	v_lshlrev_b64 v[22:23], 6, v[22:23]
	v_add_u32_e32 v24, s25, v24
	v_lshlrev_b64 v[20:21], 6, v[20:21]
	ds_read_b128 v[38:41], v240 offset:3072
	v_lshl_add_u64 v[208:209], s[40:41], 0, v[22:23]
	v_add_u32_e32 v22, 0x2d000, v24
	v_mov_b32_e32 v23, v17
	v_lshl_add_u64 v[212:213], s[40:41], 0, v[20:21]
	v_add_u32_e32 v20, 0x24000, v24
	v_mov_b32_e32 v21, v17
	s_waitcnt lgkmcnt(0)
	v_lshl_add_u64 v[22:23], v[18:19], 0, v[22:23]
	v_lshl_add_u64 v[18:19], v[18:19], 0, v[20:21]
	v_lshlrev_b64 v[22:23], 6, v[22:23]
	v_lshlrev_b64 v[18:19], 6, v[18:19]
	v_mov_b32_e32 v74, 0
	v_mov_b32_e32 v207, v17
	v_lshl_add_u64 v[210:211], s[40:41], 0, v[22:23]
	v_lshl_add_u64 v[214:215], s[40:41], 0, v[18:19]
	s_mov_b32 s42, 0
	s_mov_b32 s44, 29
	s_mov_b32 s45, 0
	v_mov_b32_e32 v75, v74
	v_mov_b32_e32 v76, v74
	v_mov_b32_e32 v77, v74
	v_mov_b32_e32 v90, v74
	v_mov_b32_e32 v91, v74
	v_mov_b32_e32 v92, v74
	v_mov_b32_e32 v93, v74
	v_mov_b32_e32 v98, v74
	v_mov_b32_e32 v99, v74
	v_mov_b32_e32 v100, v74
	v_mov_b32_e32 v101, v74
	v_mov_b32_e32 v18, v74
	v_mov_b32_e32 v19, v74
	v_mov_b32_e32 v20, v74
	v_mov_b32_e32 v21, v74
	v_mov_b32_e32 v22, v74
	v_mov_b32_e32 v23, v74
	v_mov_b32_e32 v24, v74
	v_mov_b32_e32 v25, v74
	v_mov_b32_e32 v26, v74
	v_mov_b32_e32 v27, v74
	v_mov_b32_e32 v28, v74
	v_mov_b32_e32 v29, v74
	v_mov_b32_e32 v30, v74
	v_mov_b32_e32 v31, v74
	v_mov_b32_e32 v32, v74
	v_mov_b32_e32 v33, v74
	v_mov_b32_e32 v34, v74
	v_mov_b32_e32 v35, v74
	v_mov_b32_e32 v36, v74
	v_mov_b32_e32 v37, v74
	v_mov_b32_e32 v42, v74
	v_mov_b32_e32 v43, v74
	v_mov_b32_e32 v44, v74
	v_mov_b32_e32 v45, v74
	v_mov_b32_e32 v46, v74
	v_mov_b32_e32 v47, v74
	v_mov_b32_e32 v48, v74
	v_mov_b32_e32 v49, v74
	v_mov_b32_e32 v62, v74
	v_mov_b32_e32 v63, v74
	v_mov_b32_e32 v64, v74
	v_mov_b32_e32 v65, v74
	v_mov_b32_e32 v66, v74
	v_mov_b32_e32 v67, v74
	v_mov_b32_e32 v68, v74
	v_mov_b32_e32 v69, v74
	v_mov_b32_e32 v70, v74
	v_mov_b32_e32 v71, v74
	v_mov_b32_e32 v72, v74
	v_mov_b32_e32 v73, v74
	v_mov_b32_e32 v78, v74
	v_mov_b32_e32 v79, v74
	v_mov_b32_e32 v80, v74
	v_mov_b32_e32 v81, v74
	v_mov_b32_e32 v82, v74
	v_mov_b32_e32 v83, v74
	v_mov_b32_e32 v84, v74
	v_mov_b32_e32 v85, v74
	v_mov_b32_e32 v94, v74
	v_mov_b32_e32 v95, v74
	v_mov_b32_e32 v96, v74
	v_mov_b32_e32 v97, v74
	v_mov_b32_e32 v86, v74
	v_mov_b32_e32 v87, v74
	v_mov_b32_e32 v88, v74
	v_mov_b32_e32 v89, v74
	v_mov_b32_e32 v102, v74
	v_mov_b32_e32 v103, v74
	v_mov_b32_e32 v104, v74
	v_mov_b32_e32 v105, v74
	v_mov_b32_e32 v106, v74
	v_mov_b32_e32 v107, v74
	v_mov_b32_e32 v108, v74
	v_mov_b32_e32 v109, v74
	v_mov_b32_e32 v110, v74
	v_mov_b32_e32 v111, v74
	v_mov_b32_e32 v112, v74
	v_mov_b32_e32 v113, v74
	v_mov_b32_e32 v114, v74
	v_mov_b32_e32 v115, v74
	v_mov_b32_e32 v116, v74
	v_mov_b32_e32 v117, v74
	v_mov_b32_e32 v118, v74
	v_mov_b32_e32 v119, v74
	v_mov_b32_e32 v120, v74
	v_mov_b32_e32 v121, v74
	v_mov_b32_e32 v122, v74
	v_mov_b32_e32 v123, v74
	v_mov_b32_e32 v124, v74
	v_mov_b32_e32 v125, v74
	v_mov_b32_e32 v126, v74
	v_mov_b32_e32 v127, v74
	v_mov_b32_e32 v128, v74
	v_mov_b32_e32 v129, v74
	v_mov_b32_e32 v130, v74
	v_mov_b32_e32 v131, v74
	v_mov_b32_e32 v132, v74
	v_mov_b32_e32 v133, v74
	v_mov_b32_e32 v134, v74
	v_mov_b32_e32 v135, v74
	v_mov_b32_e32 v136, v74
	v_mov_b32_e32 v137, v74
	v_mov_b32_e32 v138, v74
	v_mov_b32_e32 v139, v74
	v_mov_b32_e32 v140, v74
	v_mov_b32_e32 v141, v74
	v_mov_b32_e32 v142, v74
	v_mov_b32_e32 v143, v74
	v_mov_b32_e32 v144, v74
	v_mov_b32_e32 v145, v74
	v_mov_b32_e32 v146, v74
	v_mov_b32_e32 v147, v74
	v_mov_b32_e32 v148, v74
	v_mov_b32_e32 v149, v74
	v_mov_b32_e32 v150, v74
	v_mov_b32_e32 v151, v74
	v_mov_b32_e32 v152, v74
	v_mov_b32_e32 v153, v74
	v_mov_b32_e32 v154, v74
	v_mov_b32_e32 v155, v74
	v_mov_b32_e32 v156, v74
	v_mov_b32_e32 v157, v74
	v_mov_b32_e32 v158, v74
	v_mov_b32_e32 v159, v74
	v_mov_b32_e32 v160, v74
	v_mov_b32_e32 v161, v74
	v_readfirstlane_b32 s100, v241
	v_readfirstlane_b32 s101, v242
	s_branch .LBB0_128
.LBB0_127:
	v_mfma_f32_16x16x32_bf16 v[94:97], v[178:181], v[190:193], v[94:97]
	s_cmp_gt_u32 s45, 26
	s_cbranch_scc1 .Ldma_ipb_0
	s_add_u32 m0, s47, s100
	v_lshl_add_u64 v[244:245], v[210:211], 0, v[206:207]
	s_mov_b64 s[98:99], 0x6121000
	v_lshl_add_u64 v[246:247], v[244:245], 0, s[98:99]
	global_load_lds_dwordx4 v[246:247], off
.Ldma_ipb_0:
	s_cmp_gt_u32 s45, 26
	s_cbranch_scc1 .Ldma_ipb_1
	s_add_u32 m0, s47, s101
	v_lshl_add_u64 v[246:247], v[244:245], 0, s[22:23]
	global_load_lds_dwordx4 v[246:247], off
.Ldma_ipb_1:
	s_waitcnt lgkmcnt(0)
	s_mov_b64 s[40:41], 0x64000
	s_add_i32 s45, s45, 2
	v_mfma_f32_16x16x32_bf16 v[82:85], v[170:173], v[190:193], v[82:85]
	s_cmp_gt_u32 s45, 28
	s_cbranch_scc1 .Ldma_ipb_2
	s_add_u32 m0, s47, s100
	s_addk_i32 m0, 0x4000
	v_lshl_add_u64 v[244:245], v[208:209], 0, v[206:207]
	global_load_lds_dwordx4 v[244:245], off
.Ldma_ipb_2:
	s_add_i32 s44, s44, -2
	v_mfma_f32_16x16x32_bf16 v[78:81], v[166:169], v[190:193], v[78:81]
	s_cmp_gt_u32 s45, 28
	s_cbranch_scc1 .Ldma_ipb_3
	s_add_u32 m0, s47, s101
	s_addk_i32 m0, 0x4000
	v_lshl_add_u64 v[246:247], v[244:245], 0, s[96:97]
	global_load_lds_dwordx4 v[246:247], off
.Ldma_ipb_3:
	s_andn2_b64 vcc, exec, s[10:11]
	v_mfma_f32_16x16x32_bf16 v[70:73], v[162:165], v[190:193], v[70:73]
	v_mfma_f32_16x16x32_bf16 v[66:69], v[178:181], v[186:189], v[66:69]
	v_lshl_add_u64 v[208:209], v[208:209], 0, s[40:41]
	v_lshl_add_u64 v[210:211], v[210:211], 0, s[36:37]
	v_lshl_add_u64 v[212:213], v[212:213], 0, s[40:41]
	v_lshl_add_u64 v[214:215], v[214:215], 0, s[36:37]
	v_mfma_f32_16x16x32_bf16 v[62:65], v[170:173], v[186:189], v[62:65]
	v_mfma_f32_16x16x32_bf16 v[46:49], v[166:169], v[186:189], v[46:49]
	v_mfma_f32_16x16x32_bf16 v[42:45], v[162:165], v[186:189], v[42:45]
	v_mfma_f32_16x16x32_bf16 v[34:37], v[178:181], v[182:185], v[34:37]
	v_mfma_f32_16x16x32_bf16 v[30:33], v[170:173], v[182:185], v[30:33]
	v_mfma_f32_16x16x32_bf16 v[26:29], v[166:169], v[182:185], v[26:29]
	v_mfma_f32_16x16x32_bf16 v[22:25], v[162:165], v[182:185], v[22:25]
	v_mfma_f32_16x16x32_bf16 v[18:21], v[178:181], v[174:177], v[18:21]
	v_mfma_f32_16x16x32_bf16 v[98:101], v[170:173], v[174:177], v[98:101]
	v_mfma_f32_16x16x32_bf16 v[90:93], v[166:169], v[174:177], v[90:93]
	v_mfma_f32_16x16x32_bf16 v[74:77], v[162:165], v[174:177], v[74:77]
	s_cbranch_vccz .LBB0_148

.LBB0_134:
	s_add_i32 s10, s42, 1
	s_cmp_lg_u32 s42, 3
	s_cselect_b32 s46, s10, 0
	s_lshl_b32 s47, s46, 15
	v_or_b32_e32 v38, s47, v243
	ds_read_b128 v[178:181], v38 offset:0
	ds_read_b128 v[170:173], v38 offset:1024
	ds_read_b128 v[166:169], v38 offset:2048
	ds_read_b128 v[162:165], v38 offset:3072
	v_mfma_f32_16x16x32_bf16 v[94:97], v[0:3], v[58:61], v[94:97]
	v_add_u32_e32 v202, s47, v240
	s_cmp_lt_u32 s45, 30
	s_cselect_b64 s[40:41], -1, 0
	v_mfma_f32_16x16x32_bf16 v[82:85], v[4:7], v[58:61], v[82:85]
	s_cmp_gt_u32 s45, 29
	s_cselect_b64 s[10:11], -1, 0
	s_and_b64 vcc, exec, s[10:11]
	v_mfma_f32_16x16x32_bf16 v[78:81], v[8:11], v[58:61], v[78:81]
	s_cmp_gt_u32 s45, 27
	s_cbranch_scc1 .Ldma_ipa_0
	s_lshl_b32 m0, s42, 15
	s_add_u32 m0, m0, s100
	v_lshl_add_u64 v[244:245], v[214:215], 0, v[206:207]
	s_mov_b64 s[98:99], 0x6121000
	v_lshl_add_u64 v[246:247], v[244:245], 0, s[98:99]
	global_load_lds_dwordx4 v[246:247], off
.Ldma_ipa_0:
	v_mfma_f32_16x16x32_bf16 v[70:73], v[12:15], v[58:61], v[70:73]
	s_cmp_gt_u32 s45, 27
	s_cbranch_scc1 .Ldma_ipa_1
	s_lshl_b32 m0, s42, 15
	s_add_u32 m0, m0, s101
	v_lshl_add_u64 v[246:247], v[244:245], 0, s[22:23]
	global_load_lds_dwordx4 v[246:247], off
.Ldma_ipa_1:
	ds_read_b128 v[58:61], v202 offset:0
	v_mfma_f32_16x16x32_bf16 v[66:69], v[0:3], v[54:57], v[66:69]
	s_cmp_gt_u32 s45, 27
	s_cbranch_scc1 .Ldma_ipa_2
	s_lshl_b32 m0, s42, 15
	s_add_u32 m0, m0, s100
	s_addk_i32 m0, 0x4000
	v_lshl_add_u64 v[244:245], v[212:213], 0, v[206:207]
	global_load_lds_dwordx4 v[244:245], off
.Ldma_ipa_2:
	v_mfma_f32_16x16x32_bf16 v[62:65], v[4:7], v[54:57], v[62:65]
	s_cmp_gt_u32 s45, 27
	s_cbranch_scc1 .Ldma_ipa_3
	s_lshl_b32 m0, s42, 15
	s_add_u32 m0, m0, s101
	s_addk_i32 m0, 0x4000
	v_lshl_add_u64 v[246:247], v[244:245], 0, s[96:97]
	global_load_lds_dwordx4 v[246:247], off
.Ldma_ipa_3:
	v_mfma_f32_16x16x32_bf16 v[46:49], v[8:11], v[54:57], v[46:49]
	v_mfma_f32_16x16x32_bf16 v[42:45], v[12:15], v[54:57], v[42:45]
	ds_read_b128 v[54:57], v202 offset:1024
	v_mfma_f32_16x16x32_bf16 v[34:37], v[0:3], v[50:53], v[34:37]
	v_mfma_f32_16x16x32_bf16 v[30:33], v[4:7], v[50:53], v[30:33]
	v_mfma_f32_16x16x32_bf16 v[26:29], v[8:11], v[50:53], v[26:29]
	v_mfma_f32_16x16x32_bf16 v[22:25], v[12:15], v[50:53], v[22:25]
	ds_read_b128 v[50:53], v202 offset:2048
	ds_read_b128 v[38:41], v202 offset:3072
	s_nop 0
	s_waitcnt lgkmcnt(0)
	ds_read_b128 v[190:193], v202 offset:4096
	ds_read_b128 v[186:189], v202 offset:5120
	ds_read_b128 v[182:185], v202 offset:6144
	v_mfma_f32_16x16x32_bf16 v[18:21], v[0:3], v[174:177], v[18:21]
	v_mfma_f32_16x16x32_bf16 v[98:101], v[4:7], v[174:177], v[98:101]
	v_mfma_f32_16x16x32_bf16 v[90:93], v[8:11], v[174:177], v[90:93]
	v_mfma_f32_16x16x32_bf16 v[74:77], v[12:15], v[174:177], v[74:77]
	ds_read_b128 v[174:177], v202 offset:7168
	s_nop 0
	s_waitcnt lgkmcnt(0)
	v_mfma_f32_16x16x32_bf16 v[158:161], v[178:181], v[58:61], v[158:161]
	v_mfma_f32_16x16x32_bf16 v[154:157], v[170:173], v[58:61], v[154:157]
	v_mfma_f32_16x16x32_bf16 v[150:153], v[166:169], v[58:61], v[150:153]
	v_mfma_f32_16x16x32_bf16 v[146:149], v[162:165], v[58:61], v[146:149]
	v_mfma_f32_16x16x32_bf16 v[142:145], v[178:181], v[54:57], v[142:145]
	v_mfma_f32_16x16x32_bf16 v[138:141], v[170:173], v[54:57], v[138:141]
	v_mfma_f32_16x16x32_bf16 v[134:137], v[166:169], v[54:57], v[134:137]
	v_mfma_f32_16x16x32_bf16 v[130:133], v[162:165], v[54:57], v[130:133]
	v_mfma_f32_16x16x32_bf16 v[126:129], v[178:181], v[50:53], v[126:129]
	v_mfma_f32_16x16x32_bf16 v[122:125], v[170:173], v[50:53], v[122:125]
	v_mfma_f32_16x16x32_bf16 v[118:121], v[166:169], v[50:53], v[118:121]
	v_mfma_f32_16x16x32_bf16 v[114:117], v[162:165], v[50:53], v[114:117]
	v_mfma_f32_16x16x32_bf16 v[110:113], v[178:181], v[38:41], v[110:113]
	v_mfma_f32_16x16x32_bf16 v[106:109], v[170:173], v[38:41], v[106:109]
	v_mfma_f32_16x16x32_bf16 v[102:105], v[166:169], v[38:41], v[102:105]
	v_mfma_f32_16x16x32_bf16 v[86:89], v[162:165], v[38:41], v[86:89]
	s_cbranch_vccnz .LBB0_143
	s_min_u32 s42, s44, 2
	s_cmp_lg_u32 s42, 2
	s_mov_b64 s[42:43], -1
	s_cbranch_scc0 .LBB0_141
	s_cmp_lg_u32 s44, 1
	s_cbranch_scc0 .LBB0_138
	s_waitcnt vmcnt(0)
	s_mov_b64 s[42:43], 0

.LBB0_143:
	s_cmp_gt_u32 s45, 26
	s_barrier
.LBB0_145:
	s_add_i32 s42, s46, 1
	s_cmp_lg_u32 s46, 3
	s_cselect_b32 s42, s42, 0
	s_andn2_b64 vcc, exec, s[40:41]
	s_cbranch_vccnz .LBB0_127
	s_lshl_b32 s40, s42, 15
	v_or_b32_e32 v12, s40, v243
	ds_read_b128 v[0:3], v12 offset:0
	ds_read_b128 v[4:7], v12 offset:1024
	ds_read_b128 v[8:11], v12 offset:2048
	ds_read_b128 v[12:15], v12 offset:3072
	v_add_u32_e32 v38, s40, v240
	ds_read_b128 v[58:61], v38 offset:0
	ds_read_b128 v[54:57], v38 offset:1024
	ds_read_b128 v[50:53], v38 offset:2048
	ds_read_b128 v[38:41], v38 offset:3072
	s_branch .LBB0_127

.LBB0_273:
	s_or_b64 exec, exec, s[0:1]
	v_add_co_u32_e32 v14, vcc, 0x1000, v12
	s_waitcnt vmcnt(0)
	v_lshlrev_b32_e32 v30, 16, v19
	v_addc_co_u32_e32 v15, vcc, 0, v13, vcc
	v_add_co_u32_e32 v24, vcc, 0x3000, v12
	v_and_b32_e32 v31, 0xffff0000, v19
	s_nop 0
	v_addc_co_u32_e32 v25, vcc, 0, v13, vcc
	global_load_dwordx2 v[14:15], v[14:15], off offset:2048
	s_nop 0
	global_load_dwordx2 v[26:27], v[12:13], off
	s_nop 0
	global_load_dwordx2 v[24:25], v[24:25], off
	v_lshlrev_b32_e32 v28, 16, v18
	v_and_b32_e32 v29, 0xffff0000, v18
	v_lshlrev_b32_e32 v32, 16, v16
	v_and_b32_e32 v33, 0xffff0000, v16
	s_cmp_gt_u32 s71, 7
	s_waitcnt vmcnt(2)
	v_pk_mul_f32 v[14:15], v[14:15], v[30:31]
	s_waitcnt vmcnt(1)
	v_pk_fma_f32 v[14:15], v[26:27], v[28:29], v[14:15]
	s_waitcnt vmcnt(0)
	v_pk_fma_f32 v[14:15], v[24:25], v[32:33], v[14:15]
	s_nop 0
	v_mul_f32_e32 v16, 0xbfb8aa3b, v14
	v_mul_f32_e32 v19, 0xbfb8aa3b, v15
	v_exp_f32_e32 v18, v16
	v_exp_f32_e32 v19, v19
	s_nop 0
	v_pk_add_f32 v[18:19], v[18:19], 1.0 op_sel_hi:[1,0]
	s_nop 0
	v_div_scale_f32 v16, s[0:1], v19, v19, v15
	v_div_scale_f32 v25, s[0:1], v18, v18, v14
	v_rcp_f32_e32 v26, v16
	v_rcp_f32_e32 v27, v25
	v_div_scale_f32 v24, vcc, v15, v19, v15
	v_fma_f32 v29, -v16, v26, 1.0
	v_fma_f32 v30, -v25, v27, 1.0
	v_fmac_f32_e32 v26, v29, v26
	v_div_scale_f32 v28, s[0:1], v14, v18, v14
	v_fmac_f32_e32 v27, v30, v27
	v_mul_f32_e32 v29, v24, v26
	v_mul_f32_e32 v30, v28, v27
	v_fma_f32 v31, -v16, v29, v24
	v_fma_f32 v32, -v25, v30, v28
	v_fmac_f32_e32 v29, v31, v26
	v_fmac_f32_e32 v30, v32, v27
	v_fma_f32 v16, -v16, v29, v24
	v_fma_f32 v24, -v25, v30, v28
	v_div_fmas_f32 v16, v16, v26, v29
	s_mov_b64 vcc, s[0:1]
	v_div_fixup_f32 v15, v16, v19, v15
	v_div_fmas_f32 v16, v24, v27, v30
	v_div_fixup_f32 v14, v16, v18, v14
	s_cbranch_scc1 .LBB0_268
	v_pk_mul_f32 v[18:19], v[14:15], v[14:15]
	v_add_f32_e32 v16, v18, v19
	s_cmp_lt_u32 s71, 4
	s_waitcnt lgkmcnt(0)
	s_nop 1
	v_add_f32_dpp v16, v16, v16 quad_perm:[1,0,3,2] row_mask:0xf bank_mask:0xf
	s_nop 1
	v_add_f32_dpp v16, v16, v16 quad_perm:[2,3,0,1] row_mask:0xf bank_mask:0xf
	s_nop 1
	v_add_f32_dpp v16, v16, v16 row_half_mirror row_mask:0xf bank_mask:0xf
	s_nop 1
	v_add_f32_dpp v16, v16, v16 row_mirror row_mask:0xf bank_mask:0xf
	v_mov_b32_e32 v18, v16
	s_nop 1
	v_permlane16_swap_b32_e32 v16, v18
	v_add_f32_e32 v16, v16, v18
	v_mov_b32_e32 v18, v16
	s_nop 1
	v_permlane32_swap_b32_e32 v16, v18
	v_add_f32_e32 v16, v16, v18
	v_add_f32_e32 v16, 0x358637bd, v16
	v_cmp_gt_f32_e32 vcc, s3, v16
	v_mul_f32_e32 v18, 0x4b800000, v16
	s_nop 0
	v_cndmask_b32_e32 v16, v16, v18, vcc
	v_rsq_f32_e32 v16, v16
	s_nop 0
	v_mul_f32_e32 v18, 0x45800000, v16
	v_cndmask_b32_e32 v16, v16, v18, vcc
	s_cselect_b64 vcc, -1, 0
	v_mul_f32_e32 v18, 0x3db504f3, v16
	v_cndmask_b32_e32 v16, v16, v18, vcc
	v_pk_mul_f32 v[14:15], v[14:15], v[16:17] op_sel_hi:[1,0]
	s_branch .LBB0_268

.LBB0_399:
	s_nop 1
	v_add_u32_e32 v2, s83, v134
	v_mov_b64_e32 v[0:1], 0xe8
	v_mad_u64_u32 v[0:1], s[40:41], v2, 31, v[0:1]
	v_readfirstlane_b32 s40, v126
	v_readfirstlane_b32 s41, v127
	v_add_lshl_u32 v2, v0, v119, 2
	v_add_lshl_u32 v1, v0, v135, 2
	v_add_lshl_u32 v4, v0, v136, 2
	v_add_lshl_u32 v3, v0, v137, 2
	v_add_lshl_u32 v6, v0, v138, 2
	v_add_lshl_u32 v5, v0, v139, 2
	v_add_lshl_u32 v8, v0, v140, 2
	v_add_lshl_u32 v7, v0, v141, 2
	v_add_lshl_u32 v10, v0, v142, 2
	v_add_lshl_u32 v9, v0, v143, 2
	v_add_lshl_u32 v12, v0, v144, 2
	v_add_lshl_u32 v11, v0, v145, 2
	v_add_lshl_u32 v14, v0, v146, 2
	v_add_lshl_u32 v13, v0, v147, 2
	v_add_lshl_u32 v16, v0, v148, 2
	v_add_lshl_u32 v15, v0, v149, 2
	global_load_dword v2, v2, s[40:41]
	global_load_dword v1, v1, s[40:41]
	global_load_dword v4, v4, s[40:41]
	global_load_dword v3, v3, s[40:41]
	global_load_dword v6, v6, s[40:41]
	global_load_dword v5, v5, s[40:41]
	global_load_dword v8, v8, s[40:41]
	global_load_dword v7, v7, s[40:41]
	global_load_dword v10, v10, s[40:41]
	global_load_dword v9, v9, s[40:41]
	global_load_dword v12, v12, s[40:41]
	global_load_dword v11, v11, s[40:41]
	global_load_dword v14, v14, s[40:41]
	global_load_dword v13, v13, s[40:41]
	global_load_dword v16, v16, s[40:41]
	global_load_dword v15, v15, s[40:41]
	v_mov_b32_e32 v19, 0xff800000
	v_mul_f32_e32 v112, s94, v112
	v_mul_f32_e32 v113, s94, v113
	v_mul_f32_e32 v114, s94, v114
	v_mul_f32_e32 v115, s94, v115
	v_mul_f32_e32 v108, s94, v108
	v_mul_f32_e32 v109, s94, v109
	v_mul_f32_e32 v110, s94, v110
	v_mul_f32_e32 v111, s94, v111
	v_mul_f32_e32 v104, s94, v104
	v_mul_f32_e32 v105, s94, v105
	v_mul_f32_e32 v106, s94, v106
	v_mul_f32_e32 v107, s94, v107
	v_mul_f32_e32 v100, s94, v100
	v_mul_f32_e32 v101, s94, v101
	v_mul_f32_e32 v102, s94, v102
	v_mul_f32_e32 v103, s94, v103
	s_waitcnt vmcnt(0)
	v_mul_f32_e32 v2, s95, v2
	v_add_f32_e32 v2, v112, v2
	v_cndmask_b32_e64 v2, v19, v2, s[44:45]
	v_mul_f32_e32 v1, s95, v1
	v_add_f32_e32 v1, v113, v1
	v_cndmask_b32_e64 v1, v19, v1, s[46:47]
	v_mul_f32_e32 v4, s95, v4
	v_add_f32_e32 v4, v114, v4
	v_cndmask_b32_e64 v4, v19, v4, s[48:49]
	v_mul_f32_e32 v3, s95, v3
	v_add_f32_e32 v3, v115, v3
	v_cndmask_b32_e64 v3, v19, v3, s[50:51]
	v_mul_f32_e32 v6, s95, v6
	v_add_f32_e32 v6, v108, v6
	v_cndmask_b32_e64 v6, v19, v6, s[64:65]
	v_mul_f32_e32 v5, s95, v5
	v_add_f32_e32 v5, v109, v5
	v_cndmask_b32_e64 v5, v19, v5, s[66:67]
	v_mul_f32_e32 v8, s95, v8
	v_add_f32_e32 v8, v110, v8
	v_cndmask_b32_e64 v8, v19, v8, s[68:69]
	v_mul_f32_e32 v7, s95, v7
	v_add_f32_e32 v7, v111, v7
	v_cndmask_b32_e64 v7, v19, v7, s[70:71]
	v_mul_f32_e32 v10, s95, v10
	v_add_f32_e32 v10, v104, v10
	v_cndmask_b32_e64 v10, v19, v10, s[72:73]
	v_mul_f32_e32 v9, s95, v9
	v_add_f32_e32 v9, v105, v9
	v_cndmask_b32_e64 v9, v19, v9, s[74:75]
	v_mul_f32_e32 v12, s95, v12
	v_add_f32_e32 v12, v106, v12
	v_cndmask_b32_e64 v12, v19, v12, s[76:77]
	v_mul_f32_e32 v11, s95, v11
	v_add_f32_e32 v11, v107, v11
	v_cndmask_b32_e64 v11, v19, v11, s[0:1]
	v_mul_f32_e32 v14, s95, v14
	v_add_f32_e32 v14, v100, v14
	v_cndmask_b32_e64 v14, v19, v14, s[52:53]
	v_mul_f32_e32 v13, s95, v13
	v_add_f32_e32 v13, v101, v13
	v_cndmask_b32_e64 v13, v19, v13, s[54:55]
	v_mul_f32_e32 v16, s95, v16
	v_add_f32_e32 v16, v102, v16
	v_cndmask_b32_e64 v16, v19, v16, s[56:57]
	v_mul_f32_e32 v15, s95, v15
	v_add_f32_e32 v15, v103, v15
	v_cndmask_b32_e64 v15, v19, v15, s[58:59]
	s_mov_b32 s40, 0xff800000
	v_max3_f32 v0, v2, s40, v1
	v_max3_f32 v0, v0, v4, v3
	v_max3_f32 v0, v0, v6, v5
	v_max3_f32 v0, v0, v8, v7
	v_max3_f32 v0, v0, v10, v9
	v_max3_f32 v0, v0, v12, v11
	v_cmp_lt_i32_e32 vcc, v222, v220
	v_max3_f32 v0, v0, v14, v13
	v_max3_f32 v0, v0, v16, v15
	v_cndmask_b32_e32 v19, v218, v222, vcc
	v_lshlrev_b32_e32 v19, 2, v19
	ds_bpermute_b32 v19, v19, v0
	v_cmp_lt_i32_e32 vcc, v221, v220
	s_waitcnt lgkmcnt(0)
	v_max_f32_e32 v19, v19, v19
	v_max_f32_e32 v0, v0, v19
	v_cndmask_b32_e32 v19, v218, v221, vcc
	v_lshlrev_b32_e32 v19, 2, v19
	ds_bpermute_b32 v19, v19, v0
	s_waitcnt lgkmcnt(0)
	v_max3_f32 v19, v151, v0, v19
	v_sub_f32_e32 v0, v2, v19
	v_sub_f32_e32 v1, v1, v19
	v_exp_f32_e32 v0, v0
	v_sub_f32_e32 v2, v4, v19
	v_exp_f32_e32 v1, v1
	v_exp_f32_e32 v2, v2
	v_add_f32_e32 v4, 0, v0
	v_sub_f32_e32 v3, v3, v19
	v_add_f32_e32 v4, v1, v4
	v_add_f32_e32 v100, v2, v4
	v_exp_f32_e32 v3, v3
	v_sub_f32_e32 v4, v6, v19
	v_exp_f32_e32 v4, v4
	v_sub_f32_e32 v5, v5, v19
	v_exp_f32_e32 v5, v5
	v_sub_f32_e32 v6, v8, v19
	v_exp_f32_e32 v6, v6
	v_add_f32_e32 v8, v3, v100
	v_add_f32_e32 v8, v4, v8
	v_add_f32_e32 v8, v5, v8
	v_sub_f32_e32 v7, v7, v19
	v_add_f32_e32 v100, v6, v8
	v_exp_f32_e32 v7, v7
	v_sub_f32_e32 v8, v10, v19
	v_exp_f32_e32 v8, v8
	v_sub_f32_e32 v9, v9, v19
	v_exp_f32_e32 v9, v9
	v_sub_f32_e32 v10, v12, v19
	v_exp_f32_e32 v10, v10
	v_add_f32_e32 v12, v7, v100
	v_add_f32_e32 v12, v8, v12
	v_add_f32_e32 v12, v9, v12
	v_sub_f32_e32 v11, v11, v19
	v_add_f32_e32 v100, v10, v12
	v_exp_f32_e32 v11, v11
	v_sub_f32_e32 v12, v14, v19
	v_exp_f32_e32 v12, v12
	v_sub_f32_e32 v13, v13, v19
	v_exp_f32_e32 v13, v13
	v_sub_f32_e32 v14, v16, v19
	v_exp_f32_e32 v14, v14
	v_add_f32_e32 v16, v11, v100
	v_add_f32_e32 v16, v12, v16
	v_add_f32_e32 v16, v13, v16
	v_add_f32_e32 v152, v14, v16
	v_sub_f32_e32 v15, v15, v19
	v_sub_f32_e32 v16, v151, v19
	v_exp_f32_e32 v16, v16
	s_nop 0
	v_cmp_neq_f32_e32 vcc, 1.0, v16
	s_cbranch_vccnz .LBB0_389
	s_branch .LBB0_390

.LBB0_883:
	s_mov_b64 s[50:51], -1
	s_and_b64 vcc, exec, s[10:11]
	s_cbranch_vccz .LBB0_885
	v_add_u32_e32 v4, s25, v43
	v_mov_b64_e32 v[0:1], s[30:31]
	v_mad_i64_i32 v[0:1], s[50:51], v4, s33, v[0:1]
	v_ashrrev_i32_e32 v5, 31, v4
	v_lshl_add_u64 v[36:37], v[0:1], 0, v[16:17]
	global_load_dwordx4 v[12:15], v[36:37], off offset:1024
	global_load_dwordx4 v[8:11], v[36:37], off offset:2048
	global_load_dwordx4 v[0:3], v[36:37], off
	v_lshlrev_b64 v[4:5], 11, v[4:5]
	v_lshl_add_u64 v[4:5], v[26:27], 0, v[4:5]
	global_load_dwordx4 v[4:7], v[4:5], off
	s_nop 0
	global_load_dword v42, v[28:29], off
	v_cmp_lt_i32_e32 vcc, v221, v220
	s_waitcnt vmcnt(4)
	v_and_b32_e32 v19, 0xffff0000, v12
	v_cndmask_b32_e32 v18, v218, v221, vcc
	v_cmp_lt_i32_e32 vcc, v222, v220
	s_waitcnt vmcnt(3)
	v_and_b32_e32 v21, 0xffff0000, v8
	v_lshlrev_b32_e32 v20, 16, v8
	s_waitcnt vmcnt(2)
	v_and_b32_e32 v8, 0xffff0000, v0
	v_lshlrev_b32_e32 v0, 16, v0
	v_lshlrev_b32_e32 v49, 2, v18
	v_cndmask_b32_e32 v18, v218, v222, vcc
	v_cmp_lt_i32_e32 vcc, v223, v220
	s_waitcnt vmcnt(1)
	v_and_b32_e32 v23, 0xffff0000, v4
	v_lshlrev_b32_e32 v22, 16, v4
	v_mul_f32_e32 v4, 0xbfb8aa3b, v0
	v_lshlrev_b32_e32 v48, 2, v18
	v_cndmask_b32_e32 v18, v218, v223, vcc
	v_cmp_lt_i32_e32 vcc, v224, v220
	v_exp_f32_e32 v24, v4
	v_mul_f32_e32 v4, 0xbfb8aa3b, v8
	v_lshlrev_b32_e32 v47, 2, v18
	v_cndmask_b32_e32 v18, v218, v224, vcc
	v_cmp_lt_i32_e32 vcc, v225, v220
	v_exp_f32_e32 v25, v4
	v_lshlrev_b32_e32 v46, 2, v18
	v_cndmask_b32_e32 v18, v218, v225, vcc
	v_cmp_lt_i32_e32 vcc, v226, v220
	v_lshlrev_b32_e32 v45, 2, v18
	v_and_b32_e32 v52, 0xffff0000, v1
	v_cndmask_b32_e32 v18, v218, v226, vcc
	v_lshlrev_b32_e32 v44, 2, v18
	v_lshlrev_b32_e32 v18, 16, v12
	v_pk_add_f32 v[18:19], v[18:19], v[20:21]
	v_pk_add_f32 v[20:21], v[24:25], 1.0 op_sel_hi:[1,0]
	s_waitcnt vmcnt(0)
	v_pk_fma_f32 v[18:19], v[42:43], v[22:23], v[18:19] op_sel_hi:[0,1,1]
	v_div_scale_f32 v4, s[50:51], v21, v21, v8
	v_rcp_f32_e32 v12, v4
	v_lshlrev_b32_e32 v53, 16, v1
	v_and_b32_e32 v1, 0xffff0000, v5
	v_and_b32_e32 v51, 0xffff0000, v13
	v_fma_f32 v22, -v4, v12, 1.0
	v_fmac_f32_e32 v12, v22, v12
	v_div_scale_f32 v22, vcc, v8, v21, v8
	v_mul_f32_e32 v23, v22, v12
	v_fma_f32 v24, -v4, v23, v22
	v_fmac_f32_e32 v23, v24, v12
	v_fma_f32 v4, -v4, v23, v22
	v_div_fmas_f32 v4, v4, v12, v23
	v_div_fixup_f32 v21, v4, v21, v8
	v_div_scale_f32 v4, s[50:51], v20, v20, v0
	v_rcp_f32_e32 v8, v4
	v_lshlrev_b32_e32 v50, 16, v13
	v_and_b32_e32 v13, 0xffff0000, v9
	v_fma_f32 v12, -v4, v8, 1.0
	v_fmac_f32_e32 v8, v12, v8
	v_div_scale_f32 v12, vcc, v0, v20, v0
	v_mul_f32_e32 v22, v12, v8
	v_fma_f32 v23, -v4, v22, v12
	v_fmac_f32_e32 v22, v23, v8
	v_fma_f32 v4, -v4, v22, v12
	v_div_fmas_f32 v4, v4, v8, v22
	v_div_fixup_f32 v20, v4, v20, v0
	v_lshlrev_b32_e32 v0, 16, v5
	v_mul_f32_e32 v4, 0xbfb8aa3b, v53
	v_mul_f32_e32 v5, 0xbfb8aa3b, v52
	v_exp_f32_e32 v4, v4
	v_exp_f32_e32 v5, v5
	v_lshlrev_b32_e32 v12, 16, v9
	v_pk_add_f32 v[8:9], v[50:51], v[12:13]
	v_and_b32_e32 v51, 0xffff0000, v6
	v_pk_add_f32 v[4:5], v[4:5], 1.0 op_sel_hi:[1,0]
	v_pk_fma_f32 v[0:1], v[42:43], v[0:1], v[8:9] op_sel_hi:[0,1,1]
	v_div_scale_f32 v8, s[50:51], v5, v5, v52
	v_rcp_f32_e32 v9, v8
	v_pk_mul_f32 v[38:39], v[18:19], v[20:21]
	global_load_dwordx4 v[18:21], v[30:31], off offset:16
	global_load_dwordx4 v[22:25], v[30:31], off
	v_pk_mul_f32 v[40:41], v[38:39], v[38:39]
	v_fma_f32 v12, -v8, v9, 1.0
	v_fmac_f32_e32 v9, v12, v9
	v_div_scale_f32 v12, vcc, v52, v5, v52
	v_mul_f32_e32 v13, v12, v9
	v_fma_f32 v50, -v8, v13, v12
	v_fmac_f32_e32 v13, v50, v9
	v_fma_f32 v8, -v8, v13, v12
	v_div_fmas_f32 v8, v8, v9, v13
	v_div_fixup_f32 v5, v8, v5, v52
	v_div_scale_f32 v8, s[50:51], v4, v4, v53
	v_rcp_f32_e32 v9, v8
	s_nop 0
	v_fma_f32 v12, -v8, v9, 1.0
	v_fmac_f32_e32 v9, v12, v9
	v_div_scale_f32 v12, vcc, v53, v4, v53
	v_mul_f32_e32 v13, v12, v9
	v_fma_f32 v50, -v8, v13, v12
	v_fmac_f32_e32 v13, v50, v9
	v_fma_f32 v8, -v8, v13, v12
	v_div_fmas_f32 v8, v8, v9, v13
	v_and_b32_e32 v13, 0xffff0000, v10
	v_lshlrev_b32_e32 v12, 16, v10
	v_and_b32_e32 v10, 0xffff0000, v2
	v_lshlrev_b32_e32 v2, 16, v2
	v_lshlrev_b32_e32 v50, 16, v6
	v_mul_f32_e32 v6, 0xbfb8aa3b, v2
	v_exp_f32_e32 v52, v6
	v_mul_f32_e32 v6, 0xbfb8aa3b, v10
	v_div_fixup_f32 v4, v8, v4, v53
	v_exp_f32_e32 v53, v6
	v_and_b32_e32 v9, 0xffff0000, v14
	v_lshlrev_b32_e32 v8, 16, v14
	v_pk_add_f32 v[8:9], v[8:9], v[12:13]
	v_pk_add_f32 v[12:13], v[52:53], 1.0 op_sel_hi:[1,0]
	v_pk_fma_f32 v[8:9], v[42:43], v[50:51], v[8:9] op_sel_hi:[0,1,1]
	v_div_scale_f32 v6, s[50:51], v13, v13, v10
	v_rcp_f32_e32 v14, v6
	v_lshlrev_b32_e32 v53, 16, v3
	v_pk_mul_f32 v[0:1], v[0:1], v[4:5]
	v_fma_f32 v50, -v6, v14, 1.0
	v_fmac_f32_e32 v14, v50, v14
	v_div_scale_f32 v50, vcc, v10, v13, v10
	v_mul_f32_e32 v51, v50, v14
	v_fma_f32 v52, -v6, v51, v50
	v_fmac_f32_e32 v51, v52, v14
	v_fma_f32 v6, -v6, v51, v50
	v_div_fmas_f32 v6, v6, v14, v51
	v_div_fixup_f32 v13, v6, v13, v10
	v_div_scale_f32 v6, s[50:51], v12, v12, v2
	v_rcp_f32_e32 v10, v6
	v_and_b32_e32 v52, 0xffff0000, v3
	v_and_b32_e32 v3, 0xffff0000, v7
	v_pk_mul_f32 v[4:5], v[0:1], v[0:1]
	v_fma_f32 v14, -v6, v10, 1.0
	v_fmac_f32_e32 v10, v14, v10
	v_div_scale_f32 v14, vcc, v2, v12, v2
	v_mul_f32_e32 v50, v14, v10
	v_fma_f32 v51, -v6, v50, v14
	v_fmac_f32_e32 v50, v51, v10
	v_fma_f32 v6, -v6, v50, v14
	v_div_fmas_f32 v6, v6, v10, v50
	v_div_fixup_f32 v12, v6, v12, v2
	v_lshlrev_b32_e32 v2, 16, v7
	v_mul_f32_e32 v6, 0xbfb8aa3b, v53
	v_mul_f32_e32 v7, 0xbfb8aa3b, v52
	v_exp_f32_e32 v6, v6
	v_exp_f32_e32 v7, v7
	v_and_b32_e32 v51, 0xffff0000, v15
	v_lshlrev_b32_e32 v50, 16, v15
	v_and_b32_e32 v15, 0xffff0000, v11
	v_lshlrev_b32_e32 v14, 16, v11
	v_pk_add_f32 v[10:11], v[50:51], v[14:15]
	v_pk_add_f32 v[6:7], v[6:7], 1.0 op_sel_hi:[1,0]
	v_pk_fma_f32 v[2:3], v[42:43], v[2:3], v[10:11] op_sel_hi:[0,1,1]
	v_div_scale_f32 v10, s[50:51], v7, v7, v52
	v_rcp_f32_e32 v11, v10
	v_pk_mul_f32 v[8:9], v[8:9], v[12:13]
	v_fma_f32 v14, -v10, v11, 1.0
	v_fmac_f32_e32 v11, v14, v11
	v_div_scale_f32 v14, vcc, v52, v7, v52
	v_mul_f32_e32 v15, v14, v11
	v_fma_f32 v42, -v10, v15, v14
	v_fmac_f32_e32 v15, v42, v11
	v_fma_f32 v10, -v10, v15, v14
	v_div_fmas_f32 v10, v10, v11, v15
	v_div_fixup_f32 v7, v10, v7, v52
	v_div_scale_f32 v10, s[50:51], v6, v6, v53
	v_rcp_f32_e32 v11, v10
	v_pk_mul_f32 v[12:13], v[8:9], v[8:9]
	s_mov_b64 s[50:51], 0
	v_fma_f32 v14, -v10, v11, 1.0
	v_fmac_f32_e32 v11, v14, v11
	v_div_scale_f32 v14, vcc, v53, v6, v53
	v_mul_f32_e32 v15, v14, v11
	v_fma_f32 v42, -v10, v15, v14
	v_fmac_f32_e32 v15, v42, v11
	v_fma_f32 v10, -v10, v15, v14
	v_div_fmas_f32 v10, v10, v11, v15
	v_div_fixup_f32 v6, v10, v6, v53
	v_add_f32_e32 v10, v40, v41
	v_add_f32_e32 v4, v4, v10
	v_add_f32_e32 v4, v5, v4
	v_pk_mul_f32 v[6:7], v[2:3], v[6:7]
	v_add_f32_e32 v4, v12, v4
	v_pk_mul_f32 v[2:3], v[6:7], v[6:7]
	v_add_f32_e32 v4, v13, v4
	v_add_f32_e32 v2, v2, v4
	v_add_f32_e32 v2, v3, v2
	s_waitcnt lgkmcnt(0)
	s_nop 1
	v_add_f32_dpp v2, v2, v2 quad_perm:[1,0,3,2] row_mask:0xf bank_mask:0xf
	s_nop 1
	v_add_f32_dpp v2, v2, v2 quad_perm:[2,3,0,1] row_mask:0xf bank_mask:0xf
	s_nop 1
	v_add_f32_dpp v2, v2, v2 row_half_mirror row_mask:0xf bank_mask:0xf
	s_nop 1
	v_add_f32_dpp v2, v2, v2 row_mirror row_mask:0xf bank_mask:0xf
	v_mov_b32_e32 v3, v2
	s_nop 1
	v_permlane16_swap_b32_e32 v2, v3
	v_add_f32_e32 v2, v2, v3
	v_mov_b32_e32 v3, v2
	s_nop 1
	v_permlane32_swap_b32_e32 v2, v3
	v_add_f32_e32 v2, v2, v3
	v_fmamk_f32 v2, v2, 0x3b000000, v231
	v_cmp_gt_f32_e32 vcc, s3, v2
	v_mul_f32_e32 v3, 0x4b800000, v2
	s_nop 0
	v_cndmask_b32_e32 v2, v2, v3, vcc
	v_rsq_f32_e32 v2, v2
	s_nop 0
	v_mul_f32_e32 v3, 0x45800000, v2
	v_cndmask_b32_e32 v10, v2, v3, vcc
	v_pk_mul_f32 v[2:3], v[38:39], v[10:11] op_sel_hi:[1,0]
	v_pk_mul_f32 v[0:1], v[0:1], v[10:11] op_sel_hi:[1,0]
	s_waitcnt vmcnt(0)
	v_pk_mul_f32 v[2:3], v[22:23], v[2:3]
	v_pk_mul_f32 v[0:1], v[24:25], v[0:1]
	v_cvt_pk_bf16_f32 v2, v2, v3
	v_cvt_pk_bf16_f32 v3, v0, v1
	v_pk_mul_f32 v[0:1], v[8:9], v[10:11] op_sel_hi:[1,0]
	s_nop 0
	v_pk_mul_f32 v[0:1], v[18:19], v[0:1]
	s_nop 0
	v_cvt_pk_bf16_f32 v4, v0, v1
	v_pk_mul_f32 v[0:1], v[6:7], v[10:11] op_sel_hi:[1,0]
	s_nop 0
	v_pk_mul_f32 v[0:1], v[20:21], v[0:1]
	s_nop 0
	v_cvt_pk_bf16_f32 v5, v0, v1
	global_store_dwordx4 v[36:37], v[2:5], off offset:1024

.LBB0_887:
	v_lshl_add_u64 v[6:7], v[34:35], 0, s[50:51]
	v_add_co_u32_e32 v6, vcc, 0xa921000, v6
	s_add_u32 s50, s50, 0x100
	s_nop 0
	v_addc_co_u32_e32 v7, vcc, 0, v7, vcc
	global_load_dword v9, v[6:7], off
	global_load_dword v11, v[6:7], off offset:1024
	global_load_dword v12, v[6:7], off offset:3072
	s_addc_u32 s51, s51, 0
	s_cmpk_eq_i32 s50, 0x400
	s_waitcnt vmcnt(2)
	v_lshlrev_b32_e32 v8, 16, v9
	s_waitcnt vmcnt(1)
	v_lshlrev_b32_e32 v10, 16, v11
	s_waitcnt vmcnt(0)
	v_lshlrev_b32_e32 v18, 16, v12
	v_and_b32_e32 v19, 0xffff0000, v12
	global_load_dwordx2 v[12:13], v[32:33], off
	v_and_b32_e32 v9, 0xffff0000, v9
	v_and_b32_e32 v11, 0xffff0000, v11
	v_pk_add_f32 v[8:9], v[8:9], v[10:11]
	s_nop 0
	v_pk_mul_f32 v[10:11], v[8:9], v[8:9]
	s_nop 0
	v_add_f32_e32 v10, v10, v11
	s_waitcnt lgkmcnt(0)
	s_nop 1
	v_add_f32_dpp v10, v10, v10 quad_perm:[1,0,3,2] row_mask:0xf bank_mask:0xf
	s_nop 1
	v_add_f32_dpp v10, v10, v10 quad_perm:[2,3,0,1] row_mask:0xf bank_mask:0xf
	s_nop 1
	v_add_f32_dpp v10, v10, v10 row_half_mirror row_mask:0xf bank_mask:0xf
	s_nop 1
	v_add_f32_dpp v10, v10, v10 row_mirror row_mask:0xf bank_mask:0xf
	v_mov_b32_e32 v11, v10
	s_nop 1
	v_permlane16_swap_b32_e32 v10, v11
	v_add_f32_e32 v10, v10, v11
	v_mov_b32_e32 v11, v10
	s_nop 1
	v_permlane32_swap_b32_e32 v10, v11
	v_add_f32_e32 v10, v10, v11
	v_fmamk_f32 v10, v10, 0x3c000000, v231
	v_cmp_gt_f32_e32 vcc, s3, v10
	v_mul_f32_e32 v11, 0x4b800000, v10
	s_nop 0
	v_cndmask_b32_e32 v10, v10, v11, vcc
	v_rsq_f32_e32 v10, v10
	s_nop 0
	v_mul_f32_e32 v11, 0x45800000, v10
	v_cndmask_b32_e32 v10, v10, v11, vcc
	v_mul_f32_e32 v11, 0xbfb8aa3b, v18
	v_pk_mul_f32 v[8:9], v[8:9], v[10:11] op_sel_hi:[1,0]
	v_mul_f32_e32 v10, 0xbfb8aa3b, v19
	v_exp_f32_e32 v14, v11
	v_exp_f32_e32 v15, v10
	s_waitcnt vmcnt(0)
	v_pk_mul_f32 v[8:9], v[12:13], v[8:9]
	v_pk_add_f32 v[10:11], v[14:15], 1.0 op_sel_hi:[1,0]
	s_nop 0
	v_div_scale_f32 v12, s[52:53], v11, v11, v19
	v_rcp_f32_e32 v13, v12
	s_nop 0
	v_fma_f32 v14, -v12, v13, 1.0
	v_fmac_f32_e32 v13, v14, v13
	v_div_scale_f32 v14, vcc, v19, v11, v19
	v_mul_f32_e32 v15, v14, v13
	v_fma_f32 v20, -v12, v15, v14
	v_fmac_f32_e32 v15, v20, v13
	v_fma_f32 v12, -v12, v15, v14
	v_div_fmas_f32 v12, v12, v13, v15
	v_div_fixup_f32 v11, v12, v11, v19
	v_div_scale_f32 v12, s[52:53], v10, v10, v18
	v_rcp_f32_e32 v13, v12
	s_nop 0
	v_fma_f32 v14, -v12, v13, 1.0
	v_fmac_f32_e32 v13, v14, v13
	v_div_scale_f32 v14, vcc, v18, v10, v18
	v_mul_f32_e32 v15, v14, v13
	v_fma_f32 v19, -v12, v15, v14
	v_fmac_f32_e32 v15, v19, v13
	v_fma_f32 v12, -v12, v15, v14
	v_div_fmas_f32 v12, v12, v13, v15
	v_div_fixup_f32 v10, v12, v10, v18
	v_pk_mul_f32 v[8:9], v[10:11], v[8:9]
	s_nop 0
	v_cvt_pk_bf16_f32 v8, v8, v9
	global_store_dword v[6:7], v8, off
	s_cbranch_scc0 .LBB0_887
	s_branch .LBB0_882

.LBB0_1073:
	v_mov_b32_e32 v0, v217
	v_mov_b32_e32 v27, v217
	v_ashrrev_i32_e32 v0, 4, v0
	v_and_b32_e32 v0, -4, v0
	v_add3_u32 v12, v15, s34, v0
	v_add3_u32 v0, v0, v15, s43
	v_lshrrev_b32_e32 v0, 12, v0
	v_ashrrev_i32_e32 v13, 31, v12
	v_lshlrev_b32_e32 v94, 3, v27
	v_add_u32_e32 v4, 1, v0
	v_lshlrev_b64 v[0:1], 12, v[12:13]
	v_and_b32_e32 v14, 0x1f8, v94
	v_lshl_add_u64 v[0:1], s[18:19], 0, v[0:1]
	v_lshlrev_b64 v[2:3], 11, v[12:13]
	v_lshlrev_b32_e32 v16, 2, v14
	v_lshl_add_u64 v[2:3], s[6:7], 0, v[2:3]
	v_lshl_add_u64 v[10:11], v[0:1], 0, v[16:17]
	v_cmp_lt_i32_e64 s[0:1], s2, v12
	v_lshlrev_b32_e32 v0, 1, v14
	v_mov_b32_e32 v1, v17
	v_cndmask_b32_e64 v8, 0, v4, s[0:1]
	v_lshl_add_u64 v[4:5], v[2:3], 0, v[0:1]
	global_load_dwordx4 v[0:3], v[4:5], off
	s_nop 0
	global_load_dwordx4 v[4:7], v[4:5], off offset:1024
	v_cmp_lt_i32_e64 s[0:1], v221, v220
	v_add_u32_e32 v18, s25, v8
	v_or_b32_e32 v26, 0x200, v14
	v_cndmask_b32_e64 v9, v218, v221, s[0:1]
	v_cmp_lt_i32_e64 s[0:1], v222, v220
	v_lshlrev_b32_e32 v95, 2, v9
	v_mov_b32_e32 v19, v17
	v_cndmask_b32_e64 v9, v218, v222, s[0:1]
	v_cmp_lt_i32_e64 s[0:1], v223, v220
	v_lshlrev_b32_e32 v96, 2, v9
	s_add_i32 s34, s34, 1
	v_cndmask_b32_e64 v9, v218, v223, s[0:1]
	v_cmp_lt_i32_e64 s[0:1], v224, v220
	v_lshlrev_b32_e32 v97, 2, v9
	s_cmp_lg_u32 s34, 4
	v_cndmask_b32_e64 v9, v218, v224, s[0:1]
	v_cmp_lt_i32_e64 s[0:1], v225, v220
	v_lshlrev_b32_e32 v98, 2, v9
	s_waitcnt vmcnt(1)
	v_and_b32_e32 v69, 0xffff0000, v0
	v_cndmask_b32_e64 v9, v218, v225, s[0:1]
	v_cmp_lt_i32_e64 s[0:1], v226, v220
	v_lshlrev_b32_e32 v99, 2, v9
	v_lshlrev_b32_e32 v68, 16, v0
	v_cndmask_b32_e64 v9, v218, v226, s[0:1]
	v_lshlrev_b32_e32 v100, 2, v9
	v_mov_b64_e32 v[8:9], s[28:29]
	v_mad_u64_u32 v[8:9], s[0:1], v18, s24, v[8:9]
	v_lshl_add_u64 v[20:21], v[8:9], 0, s[50:51]
	v_lshl_add_u64 v[24:25], v[20:21], 0, v[16:17]
	v_lshlrev_b32_e32 v18, 2, v26
	v_lshl_add_u64 v[56:57], v[20:21], 0, v[18:19]
	global_load_dwordx4 v[20:23], v[10:11], off offset:16
	global_load_dwordx4 v[28:31], v[10:11], off
	global_load_dwordx4 v[32:35], v[24:25], off offset:16
	global_load_dwordx4 v[36:39], v[24:25], off
	global_load_dwordx4 v[40:43], v16, s[44:45] offset:16
	global_load_dwordx4 v[44:47], v16, s[44:45]
	v_and_b32_e32 v25, 0xffff0000, v1
	v_lshlrev_b32_e32 v24, 16, v1
	v_and_b32_e32 v75, 0xffff0000, v2
	v_lshlrev_b32_e32 v74, 16, v2
	v_and_b32_e32 v79, 0xffff0000, v3
	v_lshlrev_b32_e32 v78, 16, v3
	global_load_dwordx4 v[0:3], v[10:11], off offset:2064
	global_load_dwordx4 v[48:51], v[10:11], off offset:2048
	global_load_dwordx4 v[52:55], v[56:57], off offset:16
	s_nop 0
	global_load_dwordx4 v[56:59], v[56:57], off
	s_nop 0
	global_load_dwordx4 v[60:63], v16, s[44:45] offset:2064
	global_load_dwordx4 v[64:67], v16, s[44:45] offset:2048
	v_pk_mul_f32 v[70:71], v[68:69], v[68:69]
	v_pk_mul_f32 v[72:73], v[24:25], v[24:25]
	v_add_f32_e32 v14, v70, v71
	v_add_f32_e32 v14, v72, v14
	v_pk_mul_f32 v[76:77], v[74:75], v[74:75]
	v_add_f32_e32 v14, v73, v14
	v_add_f32_e32 v14, v76, v14
	v_pk_mul_f32 v[80:81], v[78:79], v[78:79]
	v_add_f32_e32 v14, v77, v14
	s_waitcnt vmcnt(12)
	v_and_b32_e32 v83, 0xffff0000, v4
	v_lshlrev_b32_e32 v82, 16, v4
	v_add_f32_e32 v14, v80, v14
	v_pk_mul_f32 v[84:85], v[82:83], v[82:83]
	v_add_f32_e32 v14, v81, v14
	v_and_b32_e32 v87, 0xffff0000, v5
	v_lshlrev_b32_e32 v86, 16, v5
	v_add_f32_e32 v14, v84, v14
	v_pk_mul_f32 v[4:5], v[86:87], v[86:87]
	v_add_f32_e32 v14, v85, v14
	v_and_b32_e32 v89, 0xffff0000, v6
	v_lshlrev_b32_e32 v88, 16, v6
	v_add_f32_e32 v4, v4, v14
	v_pk_mul_f32 v[90:91], v[88:89], v[88:89]
	v_add_f32_e32 v4, v5, v4
	v_and_b32_e32 v93, 0xffff0000, v7
	v_lshlrev_b32_e32 v92, 16, v7
	v_add_f32_e32 v4, v90, v4
	v_pk_mul_f32 v[6:7], v[92:93], v[92:93]
	v_add_f32_e32 v4, v91, v4
	v_add_f32_e32 v4, v6, v4
	v_add_f32_e32 v4, v7, v4
	s_waitcnt lgkmcnt(0)
	s_nop 1
	v_add_f32_dpp v4, v4, v4 quad_perm:[1,0,3,2] row_mask:0xf bank_mask:0xf
	s_nop 1
	v_add_f32_dpp v4, v4, v4 quad_perm:[2,3,0,1] row_mask:0xf bank_mask:0xf
	s_nop 1
	v_add_f32_dpp v4, v4, v4 row_half_mirror row_mask:0xf bank_mask:0xf
	s_nop 1
	v_add_f32_dpp v4, v4, v4 row_mirror row_mask:0xf bank_mask:0xf
	v_mov_b32_e32 v5, v4
	s_nop 1
	v_permlane16_swap_b32_e32 v4, v5
	v_add_f32_e32 v4, v4, v5
	v_mov_b32_e32 v5, v4
	s_nop 1
	v_permlane32_swap_b32_e32 v4, v5
	v_add_f32_e32 v4, v4, v5
	v_fmamk_f32 v4, v4, 0x3a800000, v231
	v_cmp_gt_f32_e64 s[0:1], s3, v4
	v_mul_f32_e32 v5, 0x4b800000, v4
	s_nop 0
	v_cndmask_b32_e64 v4, v4, v5, s[0:1]
	v_rsq_f32_e32 v4, v4
	s_nop 0
	v_mul_f32_e32 v5, 0x45800000, v4
	v_cndmask_b32_e64 v14, v4, v5, s[0:1]
	v_pk_mul_f32 v[4:5], v[14:15], v[68:69] op_sel_hi:[0,1]
	s_waitcnt vmcnt(6)
	v_pk_mul_f32 v[4:5], v[44:45], v[4:5]
	v_pk_mul_f32 v[6:7], v[14:15], v[86:87] op_sel_hi:[0,1]
	v_pk_fma_f32 v[28:29], v[36:37], v[4:5], v[28:29]
	v_pk_mul_f32 v[4:5], v[14:15], v[24:25] op_sel_hi:[0,1]
	v_pk_mul_f32 v[4:5], v[46:47], v[4:5]
	s_waitcnt vmcnt(0)
	v_pk_mul_f32 v[6:7], v[66:67], v[6:7]
	v_pk_fma_f32 v[30:31], v[38:39], v[4:5], v[30:31]
	v_pk_mul_f32 v[4:5], v[14:15], v[74:75] op_sel_hi:[0,1]
	v_pk_mul_f32 v[4:5], v[40:41], v[4:5]
	v_pk_fma_f32 v[6:7], v[58:59], v[6:7], v[50:51]
	v_pk_fma_f32 v[32:33], v[32:33], v[4:5], v[20:21]
	v_pk_mul_f32 v[4:5], v[14:15], v[78:79] op_sel_hi:[0,1]
	v_pk_mul_f32 v[20:21], v[14:15], v[88:89] op_sel_hi:[0,1]
	v_pk_mul_f32 v[4:5], v[42:43], v[4:5]
	v_pk_mul_f32 v[20:21], v[20:21], v[60:61]
	v_pk_fma_f32 v[34:35], v[34:35], v[4:5], v[22:23]
	v_pk_mul_f32 v[4:5], v[14:15], v[82:83] op_sel_hi:[0,1]
	v_pk_fma_f32 v[0:1], v[52:53], v[20:21], v[0:1]
	v_pk_mul_f32 v[20:21], v[14:15], v[92:93] op_sel_hi:[0,1]
	v_pk_mul_f32 v[4:5], v[64:65], v[4:5]
	v_pk_mul_f32 v[20:21], v[20:21], v[62:63]
	v_pk_fma_f32 v[4:5], v[56:57], v[4:5], v[48:49]
	v_pk_fma_f32 v[2:3], v[54:55], v[20:21], v[2:3]
	global_store_dwordx4 v[10:11], v[28:31], off
	global_store_dwordx4 v[10:11], v[32:35], off offset:16
	global_store_dwordx4 v[10:11], v[4:7], off offset:2048
	global_store_dwordx4 v[10:11], v[0:3], off offset:2064
	v_pk_mul_f32 v[10:11], v[28:29], v[28:29]
	v_pk_mul_f32 v[22:23], v[30:31], v[30:31]
	v_add_f32_e32 v10, v10, v11
	v_add_f32_e32 v10, v22, v10
	v_pk_mul_f32 v[24:25], v[32:33], v[32:33]
	v_add_f32_e32 v10, v23, v10
	v_add_f32_e32 v10, v24, v10
	v_pk_mul_f32 v[36:37], v[34:35], v[34:35]
	v_add_f32_e32 v10, v25, v10
	v_add_f32_e32 v10, v36, v10
	v_pk_mul_f32 v[38:39], v[4:5], v[4:5]
	v_add_f32_e32 v10, v37, v10
	v_add_f32_e32 v10, v38, v10
	v_pk_mul_f32 v[40:41], v[6:7], v[6:7]
	v_add_f32_e32 v10, v39, v10
	v_add_f32_e32 v10, v40, v10
	v_pk_mul_f32 v[42:43], v[0:1], v[0:1]
	v_add_f32_e32 v10, v41, v10
	v_add_f32_e32 v10, v42, v10
	v_pk_mul_f32 v[44:45], v[2:3], v[2:3]
	v_add_f32_e32 v10, v43, v10
	s_mov_b64 s[0:1], 0x3000
	v_add_f32_e32 v10, v44, v10
	v_lshl_add_u64 v[20:21], v[8:9], 0, s[0:1]
	v_add_f32_e32 v10, v45, v10
	s_mov_b64 s[0:1], 0x4000
	v_lshl_add_u64 v[24:25], v[8:9], 0, s[0:1]
	v_mov_b32_e32 v8, v10
	v_lshl_add_u64 v[22:23], v[24:25], 0, v[16:17]
	v_lshl_add_u64 v[52:53], v[20:21], 0, v[16:17]
	v_lshl_add_u64 v[24:25], v[24:25], 0, v[18:19]
	v_lshl_add_u64 v[18:19], v[20:21], 0, v[18:19]
	s_waitcnt lgkmcnt(0)
	s_nop 1
	v_add_f32_dpp v8, v8, v8 quad_perm:[1,0,3,2] row_mask:0xf bank_mask:0xf
	s_nop 1
	v_add_f32_dpp v8, v8, v8 quad_perm:[2,3,0,1] row_mask:0xf bank_mask:0xf
	s_nop 1
	v_add_f32_dpp v8, v8, v8 row_half_mirror row_mask:0xf bank_mask:0xf
	s_nop 1
	v_add_f32_dpp v8, v8, v8 row_mirror row_mask:0xf bank_mask:0xf
	v_mov_b32_e32 v9, v8
	s_nop 1
	v_permlane16_swap_b32_e32 v8, v9
	v_add_f32_e32 v8, v8, v9
	v_mov_b32_e32 v9, v8
	s_nop 1
	v_permlane32_swap_b32_e32 v8, v9
	v_add_f32_e32 v8, v8, v9
	v_fmamk_f32 v8, v8, 0x3a800000, v231
	v_cmp_gt_f32_e64 s[0:1], s3, v8
	v_mul_f32_e32 v9, 0x4b800000, v8
	s_nop 0
	v_cndmask_b32_e64 v8, v8, v9, s[0:1]
	v_rsq_f32_e32 v8, v8
	s_nop 0
	v_mul_f32_e32 v9, 0x45800000, v8
	v_cndmask_b32_e64 v14, v8, v9, s[0:1]
	global_load_dwordx4 v[36:39], v16, s[46:47] offset:16
	global_load_dwordx4 v[8:11], v16, s[46:47]
	global_load_dwordx4 v[40:43], v[22:23], off offset:16
	global_load_dwordx4 v[44:47], v[22:23], off
	global_load_dwordx4 v[48:51], v[52:53], off offset:16
	s_nop 0
	global_load_dwordx4 v[52:55], v[52:53], off
	v_pk_mul_f32 v[28:29], v[28:29], v[14:15] op_sel_hi:[1,0]
	v_pk_mul_f32 v[4:5], v[4:5], v[14:15] op_sel_hi:[1,0]
	v_pk_mul_f32 v[6:7], v[6:7], v[14:15] op_sel_hi:[1,0]
	v_pk_mul_f32 v[0:1], v[0:1], v[14:15] op_sel_hi:[1,0]
	s_waitcnt vmcnt(4)
	v_pk_mul_f32 v[8:9], v[8:9], v[28:29]
	s_waitcnt vmcnt(2)
	v_pk_add_f32 v[22:23], v[44:45], 1.0 op_sel_hi:[1,0]
	v_pk_add_f32 v[28:29], v[42:43], 1.0 op_sel_hi:[1,0]
	s_waitcnt vmcnt(0)
	v_pk_fma_f32 v[8:9], v[22:23], v[8:9], v[52:53]
	v_pk_mul_f32 v[22:23], v[30:31], v[14:15] op_sel_hi:[1,0]
	v_cvt_pk_bf16_f32 v8, v8, v9
	v_pk_mul_f32 v[10:11], v[10:11], v[22:23]
	v_pk_add_f32 v[22:23], v[46:47], 1.0 op_sel_hi:[1,0]
	s_nop 0
	v_pk_fma_f32 v[10:11], v[22:23], v[10:11], v[54:55]
	v_pk_add_f32 v[22:23], v[40:41], 1.0 op_sel_hi:[1,0]
	v_cvt_pk_bf16_f32 v9, v10, v11
	v_pk_mul_f32 v[10:11], v[32:33], v[14:15] op_sel_hi:[1,0]
	s_nop 0
	v_pk_mul_f32 v[10:11], v[10:11], v[36:37]
	s_nop 0
	v_pk_fma_f32 v[10:11], v[10:11], v[22:23], v[48:49]
	v_pk_mul_f32 v[22:23], v[34:35], v[14:15] op_sel_hi:[1,0]
	v_cvt_pk_bf16_f32 v10, v10, v11
	v_pk_mul_f32 v[22:23], v[22:23], v[38:39]
	s_nop 0
	v_pk_fma_f32 v[22:23], v[22:23], v[28:29], v[50:51]
	s_nop 0
	v_cvt_pk_bf16_f32 v11, v22, v23
	v_bfe_u32 v22, v94, 5, 4
	v_mul_u32_u24_e32 v22, 0x9000, v22
	v_mov_b32_e32 v23, v17
	v_lshl_add_u64 v[22:23], v[22:23], 0, v[12:13]
	v_lshlrev_b64 v[22:23], 6, v[22:23]
	v_lshl_add_u64 v[28:29], s[4:5], 0, v[22:23]
	v_lshlrev_b32_e32 v22, 4, v27
	v_and_b32_e32 v22, 48, v22
	v_mov_b32_e32 v23, v17
	v_lshl_add_u64 v[28:29], v[28:29], 0, v[22:23]
	global_store_dwordx4 v[28:29], v[8:11], off
	global_load_dwordx4 v[8:11], v16, s[46:47] offset:2064
	s_nop 0
	global_load_dwordx4 v[28:31], v16, s[46:47] offset:2048
	global_load_dwordx4 v[32:35], v[24:25], off offset:16
	global_load_dwordx4 v[36:39], v[24:25], off
	global_load_dwordx4 v[40:43], v[18:19], off offset:16
	s_nop 0
	global_load_dwordx4 v[18:21], v[18:19], off
	s_waitcnt vmcnt(5)
	v_pk_mul_f32 v[0:1], v[0:1], v[8:9]
	s_waitcnt vmcnt(4)
	v_pk_mul_f32 v[4:5], v[4:5], v[28:29]
	s_waitcnt vmcnt(2)
	v_pk_add_f32 v[24:25], v[36:37], 1.0 op_sel_hi:[1,0]
	v_pk_mul_f32 v[6:7], v[6:7], v[30:31]
	s_waitcnt vmcnt(0)
	v_pk_fma_f32 v[4:5], v[4:5], v[24:25], v[18:19]
	v_pk_add_f32 v[18:19], v[38:39], 1.0 op_sel_hi:[1,0]
	v_cvt_pk_bf16_f32 v4, v4, v5
	v_pk_fma_f32 v[6:7], v[6:7], v[18:19], v[20:21]
	s_nop 0
	v_cvt_pk_bf16_f32 v5, v6, v7
	v_pk_add_f32 v[6:7], v[32:33], 1.0 op_sel_hi:[1,0]
	s_nop 0
	v_pk_fma_f32 v[0:1], v[0:1], v[6:7], v[40:41]
	s_nop 0
	v_cvt_pk_bf16_f32 v6, v0, v1
	v_pk_mul_f32 v[0:1], v[2:3], v[14:15] op_sel_hi:[1,0]
	v_pk_add_f32 v[2:3], v[34:35], 1.0 op_sel_hi:[1,0]
	v_pk_mul_f32 v[0:1], v[0:1], v[10:11]
	s_nop 0
	v_pk_fma_f32 v[0:1], v[0:1], v[2:3], v[42:43]
	s_nop 0
	v_cvt_pk_bf16_f32 v7, v0, v1
	v_lshrrev_b32_e32 v0, 5, v26
	v_mul_u32_u24_e32 v16, 0x9000, v0
	v_lshl_add_u64 v[0:1], v[16:17], 0, v[12:13]
	v_lshlrev_b64 v[0:1], 6, v[0:1]
	v_lshl_add_u64 v[0:1], s[4:5], 0, v[0:1]
	v_lshl_add_u64 v[0:1], v[0:1], 0, v[22:23]
	global_store_dwordx4 v[0:1], v[4:7], off
	s_cbranch_scc1 .LBB0_1073
	s_branch .LBB0_1066

.LBB0_1152:
	s_or_b64 exec, exec, s[40:41]
	s_waitcnt lgkmcnt(0)
	s_barrier
	ds_read_b32 v0, v230
	s_waitcnt lgkmcnt(0)
	v_cmp_gt_i32_e32 vcc, 0, v0
	v_readfirstlane_b32 s40, v0
	s_cbranch_vccnz .LBB0_1174
	v_mov_b32_e32 v203, v195
	s_lshl_b32 s34, s40, 2
	s_lshl_b32 s40, s40, 8
	s_and_b32 s43, s40, 0x3f00
	v_lshrrev_b32_e32 v1, 1, v203
	s_movk_i32 s40, 0x78
	v_and_b32_e32 v1, 6, v1
	v_bfe_u32 v201, v203, 4, 2
	v_lshrrev_b32_e64 v1, v1, s40
	v_bitop3_b32 v1, v1, v201, 3 bitop3:0x6c
	v_lshlrev_b32_e32 v0, 1, v201
	v_lshlrev_b32_e32 v20, 4, v1
	v_ashrrev_i32_e32 v1, 1, v203
	v_ashrrev_i32_e32 v10, 6, v203
	v_lshrrev_b32_e64 v18, v0, s40
	v_and_b32_e32 v238, 15, v203
	v_and_b32_e32 v239, 0xffffff80, v1
	s_and_b32 s34, s34, 0x7fffff00
	v_xor_b32_e32 v0, v18, v203
	v_bfe_u32 v19, v203, 2, 4
	v_or_b32_e32 v1, v239, v238
	v_lshlrev_b32_e32 v4, 4, v10
	v_lshl_or_b32 v240, v1, 6, v20
	v_lshlrev_b32_e32 v1, 6, v203
	v_lshlrev_b32_e32 v0, 4, v0
	v_ashrrev_i32_e32 v5, 31, v4
	v_or_b32_e32 v6, s34, v19
	v_mov_b32_e32 v7, v17
	v_and_b32_e32 v21, 0x33c0, v1
	v_and_b32_e32 v0, 48, v0
	v_mov_b32_e32 v1, v17
	v_lshl_add_u64 v[8:9], v[6:7], 0, v[4:5]
	v_lshlrev_b32_e32 v241, 10, v10
	v_lshl_add_u64 v[2:3], s[4:5], 0, v[0:1]
	v_lshlrev_b64 v[8:9], 6, v[8:9]
	v_readfirstlane_b32 s40, v241
	v_lshl_add_u64 v[8:9], v[2:3], 0, v[8:9]
	s_mov_b32 m0, s40
	v_add_u32_e32 v12, 8, v10
	global_load_lds_dwordx4 v[8:9], off
	v_lshlrev_b32_e32 v8, 4, v12
	v_ashrrev_i32_e32 v9, 31, v8
	v_lshl_add_u64 v[10:11], v[6:7], 0, v[8:9]
	v_lshlrev_b32_e32 v242, 10, v12
	v_lshlrev_b64 v[10:11], 6, v[10:11]
	v_readfirstlane_b32 s40, v242
	v_lshl_add_u64 v[10:11], v[2:3], 0, v[10:11]
	s_mov_b32 m0, s40
	v_add_u32_e32 v7, 0x4000, v241
	global_load_lds_dwordx4 v[10:11], off
	v_or_b32_e32 v10, s43, v19
	v_mov_b32_e32 v11, v17
	v_lshl_add_u64 v[12:13], v[10:11], 0, v[4:5]
	v_lshl_add_u64 v[0:1], s[58:59], 0, v[0:1]
	v_lshlrev_b64 v[12:13], 6, v[12:13]
	v_readfirstlane_b32 s40, v7
	v_lshl_add_u64 v[12:13], v[0:1], 0, v[12:13]
	s_mov_b32 m0, s40
	v_add_u32_e32 v7, 0x4000, v242
	global_load_lds_dwordx4 v[12:13], off
	v_lshl_add_u64 v[12:13], v[10:11], 0, v[8:9]
	v_lshlrev_b64 v[12:13], 6, v[12:13]
	v_readfirstlane_b32 s40, v7
	v_lshl_add_u64 v[12:13], v[0:1], 0, v[12:13]
	s_mov_b32 m0, s40
	s_add_i32 s40, s34, 0x9000
	global_load_lds_dwordx4 v[12:13], off
	v_or_b32_e32 v12, s40, v19
	v_mov_b32_e32 v13, v17
	v_lshl_add_u64 v[14:15], v[12:13], 0, v[4:5]
	v_add_u32_e32 v7, 0x8000, v241
	v_lshlrev_b64 v[14:15], 6, v[14:15]
	v_readfirstlane_b32 s40, v7
	v_lshl_add_u64 v[12:13], v[12:13], 0, v[8:9]
	v_add_u32_e32 v7, 0x8000, v242
	v_lshl_add_u64 v[14:15], v[2:3], 0, v[14:15]
	s_mov_b32 m0, s40
	v_lshlrev_b64 v[12:13], 6, v[12:13]
	v_readfirstlane_b32 s40, v7
	global_load_lds_dwordx4 v[14:15], off
	v_lshl_add_u64 v[12:13], v[2:3], 0, v[12:13]
	s_mov_b32 m0, s40
	s_add_i32 s40, s43, 0x1000
	global_load_lds_dwordx4 v[12:13], off
	v_or_b32_e32 v12, s40, v19
	v_mov_b32_e32 v13, v17
	v_lshl_add_u64 v[14:15], v[12:13], 0, v[4:5]
	v_add_u32_e32 v7, 0xc000, v241
	v_lshlrev_b64 v[14:15], 6, v[14:15]
	v_readfirstlane_b32 s40, v7
	v_lshl_add_u64 v[12:13], v[12:13], 0, v[8:9]
	v_add_u32_e32 v7, 0xc000, v242
	v_lshl_add_u64 v[14:15], v[0:1], 0, v[14:15]
	s_mov_b32 m0, s40
	v_lshlrev_b64 v[12:13], 6, v[12:13]
	v_readfirstlane_b32 s40, v7
	global_load_lds_dwordx4 v[14:15], off
	v_lshl_add_u64 v[12:13], v[0:1], 0, v[12:13]
	s_mov_b32 m0, s40
	s_add_i32 s40, s34, 0x12000
	global_load_lds_dwordx4 v[12:13], off
	v_or_b32_e32 v12, s40, v19
	v_mov_b32_e32 v13, v17
	v_lshl_add_u64 v[14:15], v[12:13], 0, v[4:5]
	v_add_u32_e32 v7, 0x10000, v241
	v_lshlrev_b64 v[14:15], 6, v[14:15]
	v_readfirstlane_b32 s40, v7
	v_lshl_add_u64 v[12:13], v[12:13], 0, v[8:9]
	v_add_u32_e32 v7, 0x10000, v242
	v_lshl_add_u64 v[14:15], v[2:3], 0, v[14:15]
	s_mov_b32 m0, s40
	v_lshlrev_b64 v[12:13], 6, v[12:13]
	v_readfirstlane_b32 s40, v7
	global_load_lds_dwordx4 v[14:15], off
	v_lshl_add_u64 v[12:13], v[2:3], 0, v[12:13]
	s_mov_b32 m0, s40
	s_add_i32 s40, s43, 0x2000
	global_load_lds_dwordx4 v[12:13], off
	v_or_b32_e32 v12, s40, v19
	v_mov_b32_e32 v13, v17
	v_lshl_add_u64 v[14:15], v[12:13], 0, v[4:5]
	v_add_u32_e32 v7, 0x14000, v241
	v_lshlrev_b64 v[14:15], 6, v[14:15]
	v_readfirstlane_b32 s40, v7
	v_lshl_add_u64 v[12:13], v[12:13], 0, v[8:9]
	v_add_u32_e32 v7, 0x14000, v242
	v_lshl_add_u64 v[14:15], v[0:1], 0, v[14:15]
	s_mov_b32 m0, s40
	v_lshlrev_b64 v[12:13], 6, v[12:13]
	v_readfirstlane_b32 s40, v7
	global_load_lds_dwordx4 v[14:15], off
	v_lshl_add_u64 v[12:13], v[0:1], 0, v[12:13]
	s_mov_b32 m0, s40
	s_add_i32 s40, s34, 0x1b000
	global_load_lds_dwordx4 v[12:13], off
	v_or_b32_e32 v12, s40, v19
	v_mov_b32_e32 v13, v17
	v_lshl_add_u64 v[14:15], v[12:13], 0, v[4:5]
	v_add_u32_e32 v7, 0x18000, v241
	v_lshlrev_b64 v[14:15], 6, v[14:15]
	v_readfirstlane_b32 s40, v7
	v_lshl_add_u64 v[12:13], v[12:13], 0, v[8:9]
	v_add_u32_e32 v7, 0x18000, v242
	v_lshl_add_u64 v[14:15], v[2:3], 0, v[14:15]
	s_mov_b32 m0, s40
	v_lshlrev_b64 v[12:13], 6, v[12:13]
	v_readfirstlane_b32 s40, v7
	global_load_lds_dwordx4 v[14:15], off
	v_lshl_add_u64 v[2:3], v[2:3], 0, v[12:13]
	s_mov_b32 m0, s40
	s_add_i32 s40, s43, 0x3000
	global_load_lds_dwordx4 v[2:3], off
	v_or_b32_e32 v2, s40, v19
	v_mov_b32_e32 v3, v17
	v_lshl_add_u64 v[12:13], v[2:3], 0, v[4:5]
	v_lshl_add_u64 v[2:3], v[2:3], 0, v[8:9]
	v_lshlrev_b64 v[12:13], 6, v[12:13]
	v_add_u32_e32 v7, 0x1c000, v241
	v_lshlrev_b64 v[2:3], 6, v[2:3]
	v_lshl_add_u64 v[12:13], v[0:1], 0, v[12:13]
	v_readfirstlane_b32 s40, v7
	v_lshl_add_u64 v[0:1], v[0:1], 0, v[2:3]
	v_add_u32_e32 v2, 0x1c000, v242
	s_mov_b32 m0, s40
	v_readfirstlane_b32 s40, v2
	global_load_lds_dwordx4 v[12:13], off
	s_mov_b32 m0, s40
	s_movk_i32 s40, 0x4000
	global_load_lds_dwordx4 v[0:1], off
	v_bitop3_b32 v0, v18, 3, v203 bitop3:0x48
	v_lshlrev_b32_e32 v206, 4, v0
	v_add_u32_e32 v0, 0x5000, v10
	v_mov_b32_e32 v1, v17
	v_or3_b32 v243, v21, v20, s40
	v_lshl_add_u64 v[0:1], v[4:5], 0, v[0:1]
	v_readlane_b32 s40, v252, 19
	s_waitcnt vmcnt(12)
	s_barrier
	ds_read_b128 v[70:73], v243 offset:0
	v_lshlrev_b64 v[0:1], 6, v[0:1]
	v_readlane_b32 s41, v252, 20
	ds_read_b128 v[78:81], v243 offset:1024
	ds_read_b128 v[82:85], v243 offset:2048
	ds_read_b128 v[86:89], v243 offset:3072
	ds_read_b128 v[130:133], v240 offset:0
	ds_read_b128 v[126:129], v240 offset:1024
	s_nop 1
	v_lshl_add_u64 v[208:209], s[40:41], 0, v[0:1]
	v_add_u32_e32 v0, 0x2d000, v6
	v_mov_b32_e32 v1, v17
	v_lshl_add_u64 v[0:1], v[4:5], 0, v[0:1]
	v_lshlrev_b64 v[0:1], 6, v[0:1]
	v_lshl_add_u64 v[210:211], s[40:41], 0, v[0:1]
	v_or_b32_e32 v0, 0x4000, v10
	v_mov_b32_e32 v1, v17
	v_lshl_add_u64 v[0:1], v[4:5], 0, v[0:1]
	ds_read_b128 v[122:125], v240 offset:2048
	v_lshlrev_b64 v[0:1], 6, v[0:1]
	ds_read_b128 v[118:121], v240 offset:3072
	v_lshl_add_u64 v[212:213], s[40:41], 0, v[0:1]
	v_add_u32_e32 v0, 0x24000, v6
	v_mov_b32_e32 v1, v17
	s_waitcnt lgkmcnt(0)
	v_lshl_add_u64 v[0:1], v[4:5], 0, v[0:1]
	v_lshlrev_b64 v[0:1], 6, v[0:1]
	v_mov_b32_e32 v8, 0
	v_mov_b32_e32 v207, v17
	v_lshl_add_u64 v[214:215], s[40:41], 0, v[0:1]
	s_mov_b32 s46, 0
	s_mov_b32 s48, 29
	s_mov_b32 s49, 0
	v_mov_b32_e32 v9, v8
	v_mov_b32_e32 v10, v8
	v_mov_b32_e32 v11, v8
	v_mov_b32_e32 v22, v8
	v_mov_b32_e32 v23, v8
	v_mov_b32_e32 v24, v8
	v_mov_b32_e32 v25, v8
	v_mov_b32_e32 v26, v8
	v_mov_b32_e32 v27, v8
	v_mov_b32_e32 v28, v8
	v_mov_b32_e32 v29, v8
	v_mov_b32_e32 v0, v8
	v_mov_b32_e32 v1, v8
	v_mov_b32_e32 v2, v8
	v_mov_b32_e32 v3, v8
	v_mov_b32_e32 v4, v8
	v_mov_b32_e32 v5, v8
	v_mov_b32_e32 v6, v8
	v_mov_b32_e32 v7, v8
	v_mov_b32_e32 v12, v8
	v_mov_b32_e32 v13, v8
	v_mov_b32_e32 v14, v8
	v_mov_b32_e32 v15, v8
	v_mov_b32_e32 v18, v8
	v_mov_b32_e32 v19, v8
	v_mov_b32_e32 v20, v8
	v_mov_b32_e32 v21, v8
	v_mov_b32_e32 v30, v8
	v_mov_b32_e32 v31, v8
	v_mov_b32_e32 v32, v8
	v_mov_b32_e32 v33, v8
	v_mov_b32_e32 v34, v8
	v_mov_b32_e32 v35, v8
	v_mov_b32_e32 v36, v8
	v_mov_b32_e32 v37, v8
	v_mov_b32_e32 v38, v8
	v_mov_b32_e32 v39, v8
	v_mov_b32_e32 v40, v8
	v_mov_b32_e32 v41, v8
	v_mov_b32_e32 v42, v8
	v_mov_b32_e32 v43, v8
	v_mov_b32_e32 v44, v8
	v_mov_b32_e32 v45, v8
	v_mov_b32_e32 v46, v8
	v_mov_b32_e32 v47, v8
	v_mov_b32_e32 v48, v8
	v_mov_b32_e32 v49, v8
	v_mov_b32_e32 v50, v8
	v_mov_b32_e32 v51, v8
	v_mov_b32_e32 v52, v8
	v_mov_b32_e32 v53, v8
	v_mov_b32_e32 v54, v8
	v_mov_b32_e32 v55, v8
	v_mov_b32_e32 v56, v8
	v_mov_b32_e32 v57, v8
	v_mov_b32_e32 v58, v8
	v_mov_b32_e32 v59, v8
	v_mov_b32_e32 v60, v8
	v_mov_b32_e32 v61, v8
	v_mov_b32_e32 v62, v8
	v_mov_b32_e32 v63, v8
	v_mov_b32_e32 v64, v8
	v_mov_b32_e32 v65, v8
	v_mov_b32_e32 v66, v8
	v_mov_b32_e32 v67, v8
	v_mov_b32_e32 v68, v8
	v_mov_b32_e32 v69, v8
	v_mov_b32_e32 v74, v8
	v_mov_b32_e32 v75, v8
	v_mov_b32_e32 v76, v8
	v_mov_b32_e32 v77, v8
	v_mov_b32_e32 v90, v8
	v_mov_b32_e32 v91, v8
	v_mov_b32_e32 v92, v8
	v_mov_b32_e32 v93, v8
	v_mov_b32_e32 v94, v8
	v_mov_b32_e32 v95, v8
	v_mov_b32_e32 v96, v8
	v_mov_b32_e32 v97, v8
	v_mov_b32_e32 v98, v8
	v_mov_b32_e32 v99, v8
	v_mov_b32_e32 v100, v8
	v_mov_b32_e32 v101, v8
	v_mov_b32_e32 v102, v8
	v_mov_b32_e32 v103, v8
	v_mov_b32_e32 v104, v8
	v_mov_b32_e32 v105, v8
	v_mov_b32_e32 v106, v8
	v_mov_b32_e32 v107, v8
	v_mov_b32_e32 v108, v8
	v_mov_b32_e32 v109, v8
	v_mov_b32_e32 v110, v8
	v_mov_b32_e32 v111, v8
	v_mov_b32_e32 v112, v8
	v_mov_b32_e32 v113, v8
	v_mov_b32_e32 v114, v8
	v_mov_b32_e32 v115, v8
	v_mov_b32_e32 v116, v8
	v_mov_b32_e32 v117, v8
	v_mov_b32_e32 v134, v8
	v_mov_b32_e32 v135, v8
	v_mov_b32_e32 v136, v8
	v_mov_b32_e32 v137, v8
	v_mov_b32_e32 v138, v8
	v_mov_b32_e32 v139, v8
	v_mov_b32_e32 v140, v8
	v_mov_b32_e32 v141, v8
	v_mov_b32_e32 v142, v8
	v_mov_b32_e32 v143, v8
	v_mov_b32_e32 v144, v8
	v_mov_b32_e32 v145, v8
	v_mov_b32_e32 v146, v8
	v_mov_b32_e32 v147, v8
	v_mov_b32_e32 v148, v8
	v_mov_b32_e32 v149, v8
	v_mov_b32_e32 v150, v8
	v_mov_b32_e32 v151, v8
	v_mov_b32_e32 v152, v8
	v_mov_b32_e32 v153, v8
	v_mov_b32_e32 v154, v8
	v_mov_b32_e32 v155, v8
	v_mov_b32_e32 v156, v8
	v_mov_b32_e32 v157, v8
	v_mov_b32_e32 v158, v8
	v_mov_b32_e32 v159, v8
	v_mov_b32_e32 v160, v8
	v_mov_b32_e32 v161, v8
	v_readfirstlane_b32 s100, v241
	v_readfirstlane_b32 s101, v242
	s_branch .LBB0_1155
.LBB0_1154:
	v_mfma_f32_16x16x32_bf16 v[62:65], v[178:181], v[190:193], v[62:65]
	s_cmp_gt_u32 s49, 26
	s_cbranch_scc1 .Ldma_m1b_0
	s_add_u32 m0, s51, s100
	v_lshl_add_u64 v[244:245], v[210:211], 0, v[206:207]
	s_mov_b64 s[98:99], 0x6121000
	v_lshl_add_u64 v[246:247], v[244:245], 0, s[98:99]
	global_load_lds_dwordx4 v[246:247], off
.Ldma_m1b_0:
	s_cmp_gt_u32 s49, 26
	s_cbranch_scc1 .Ldma_m1b_1
	s_add_u32 m0, s51, s101
	v_lshl_add_u64 v[246:247], v[244:245], 0, s[22:23]
	global_load_lds_dwordx4 v[246:247], off
.Ldma_m1b_1:
	s_waitcnt lgkmcnt(0)
	s_add_i32 s49, s49, 2
	v_mfma_f32_16x16x32_bf16 v[58:61], v[170:173], v[190:193], v[58:61]
	s_cmp_gt_u32 s49, 28
	s_cbranch_scc1 .Ldma_m1b_2
	s_add_u32 m0, s51, s100
	s_addk_i32 m0, 0x4000
	v_lshl_add_u64 v[244:245], v[208:209], 0, v[206:207]
	s_mov_b64 s[98:99], 0x840000
	v_lshl_add_u64 v[246:247], v[244:245], 0, s[98:99]
	global_load_lds_dwordx4 v[246:247], off
.Ldma_m1b_2:
	s_add_i32 s48, s48, -2
	v_mfma_f32_16x16x32_bf16 v[54:57], v[166:169], v[190:193], v[54:57]
	s_cmp_gt_u32 s49, 28
	s_cbranch_scc1 .Ldma_m1b_3
	s_add_u32 m0, s51, s101
	s_addk_i32 m0, 0x4000
	s_mov_b64 s[98:99], 0x842000
	v_lshl_add_u64 v[246:247], v[244:245], 0, s[98:99]
	global_load_lds_dwordx4 v[246:247], off
.Ldma_m1b_3:
	s_andn2_b64 vcc, exec, s[40:41]
	v_mfma_f32_16x16x32_bf16 v[50:53], v[162:165], v[190:193], v[50:53]
	v_mfma_f32_16x16x32_bf16 v[46:49], v[178:181], v[186:189], v[46:49]
	v_lshl_add_u64 v[208:209], v[208:209], 0, s[26:27]
	v_lshl_add_u64 v[210:211], v[210:211], 0, s[36:37]
	v_lshl_add_u64 v[212:213], v[212:213], 0, s[26:27]
	v_lshl_add_u64 v[214:215], v[214:215], 0, s[36:37]
	v_mfma_f32_16x16x32_bf16 v[42:45], v[170:173], v[186:189], v[42:45]
	v_mfma_f32_16x16x32_bf16 v[38:41], v[166:169], v[186:189], v[38:41]
	v_mfma_f32_16x16x32_bf16 v[34:37], v[162:165], v[186:189], v[34:37]
	v_mfma_f32_16x16x32_bf16 v[30:33], v[178:181], v[182:185], v[30:33]
	v_mfma_f32_16x16x32_bf16 v[18:21], v[170:173], v[182:185], v[18:21]
	v_mfma_f32_16x16x32_bf16 v[12:15], v[166:169], v[182:185], v[12:15]
	v_mfma_f32_16x16x32_bf16 v[4:7], v[162:165], v[182:185], v[4:7]
	v_mfma_f32_16x16x32_bf16 v[0:3], v[178:181], v[174:177], v[0:3]
	v_mfma_f32_16x16x32_bf16 v[26:29], v[170:173], v[174:177], v[26:29]
	v_mfma_f32_16x16x32_bf16 v[22:25], v[166:169], v[174:177], v[22:25]
	v_mfma_f32_16x16x32_bf16 v[8:11], v[162:165], v[174:177], v[8:11]
	s_cbranch_vccz .LBB0_1141

.LBB0_1161:
	s_add_i32 s40, s46, 1
	s_cmp_lg_u32 s46, 3
	s_cselect_b32 s50, s40, 0
	s_lshl_b32 s51, s50, 15
	v_or_b32_e32 v118, s51, v243
	ds_read_b128 v[178:181], v118 offset:0
	ds_read_b128 v[170:173], v118 offset:1024
	ds_read_b128 v[166:169], v118 offset:2048
	ds_read_b128 v[162:165], v118 offset:3072
	v_mfma_f32_16x16x32_bf16 v[62:65], v[70:73], v[130:133], v[62:65]
	v_add_u32_e32 v202, s51, v240
	s_cmp_lt_u32 s49, 30
	s_cselect_b64 s[44:45], -1, 0
	v_mfma_f32_16x16x32_bf16 v[58:61], v[78:81], v[130:133], v[58:61]
	s_cmp_gt_u32 s49, 29
	s_cselect_b64 s[40:41], -1, 0
	s_and_b64 vcc, exec, s[40:41]
	v_mfma_f32_16x16x32_bf16 v[54:57], v[82:85], v[130:133], v[54:57]
	s_cmp_gt_u32 s49, 27
	s_cbranch_scc1 .Ldma_m1a_0
	s_lshl_b32 m0, s46, 15
	s_add_u32 m0, m0, s100
	v_lshl_add_u64 v[244:245], v[214:215], 0, v[206:207]
	s_mov_b64 s[98:99], 0x6121000
	v_lshl_add_u64 v[246:247], v[244:245], 0, s[98:99]
	global_load_lds_dwordx4 v[246:247], off
.Ldma_m1a_0:
	v_mfma_f32_16x16x32_bf16 v[50:53], v[86:89], v[130:133], v[50:53]
	s_cmp_gt_u32 s49, 27
	s_cbranch_scc1 .Ldma_m1a_1
	s_lshl_b32 m0, s46, 15
	s_add_u32 m0, m0, s101
	v_lshl_add_u64 v[246:247], v[244:245], 0, s[22:23]
	global_load_lds_dwordx4 v[246:247], off
.Ldma_m1a_1:
	ds_read_b128 v[130:133], v202 offset:0
	v_mfma_f32_16x16x32_bf16 v[46:49], v[70:73], v[126:129], v[46:49]
	s_cmp_gt_u32 s49, 27
	s_cbranch_scc1 .Ldma_m1a_2
	s_lshl_b32 m0, s46, 15
	s_add_u32 m0, m0, s100
	s_addk_i32 m0, 0x4000
	v_lshl_add_u64 v[244:245], v[212:213], 0, v[206:207]
	s_mov_b64 s[98:99], 0x840000
	v_lshl_add_u64 v[246:247], v[244:245], 0, s[98:99]
	global_load_lds_dwordx4 v[246:247], off
.Ldma_m1a_2:
	v_mfma_f32_16x16x32_bf16 v[42:45], v[78:81], v[126:129], v[42:45]
	s_cmp_gt_u32 s49, 27
	s_cbranch_scc1 .Ldma_m1a_3
	s_lshl_b32 m0, s46, 15
	s_add_u32 m0, m0, s101
	s_addk_i32 m0, 0x4000
	s_mov_b64 s[98:99], 0x842000
	v_lshl_add_u64 v[246:247], v[244:245], 0, s[98:99]
	global_load_lds_dwordx4 v[246:247], off
.Ldma_m1a_3:
	v_mfma_f32_16x16x32_bf16 v[38:41], v[82:85], v[126:129], v[38:41]
	v_mfma_f32_16x16x32_bf16 v[34:37], v[86:89], v[126:129], v[34:37]
	ds_read_b128 v[126:129], v202 offset:1024
	v_mfma_f32_16x16x32_bf16 v[30:33], v[70:73], v[122:125], v[30:33]
	v_mfma_f32_16x16x32_bf16 v[18:21], v[78:81], v[122:125], v[18:21]
	v_mfma_f32_16x16x32_bf16 v[12:15], v[82:85], v[122:125], v[12:15]
	v_mfma_f32_16x16x32_bf16 v[4:7], v[86:89], v[122:125], v[4:7]
	ds_read_b128 v[122:125], v202 offset:2048
	ds_read_b128 v[118:121], v202 offset:3072
	s_nop 0
	s_waitcnt lgkmcnt(0)
	ds_read_b128 v[190:193], v202 offset:4096
	ds_read_b128 v[186:189], v202 offset:5120
	ds_read_b128 v[182:185], v202 offset:6144
	v_mfma_f32_16x16x32_bf16 v[0:3], v[70:73], v[174:177], v[0:3]
	v_mfma_f32_16x16x32_bf16 v[26:29], v[78:81], v[174:177], v[26:29]
	v_mfma_f32_16x16x32_bf16 v[22:25], v[82:85], v[174:177], v[22:25]
	v_mfma_f32_16x16x32_bf16 v[8:11], v[86:89], v[174:177], v[8:11]
	ds_read_b128 v[174:177], v202 offset:7168
	s_nop 0
	s_waitcnt lgkmcnt(0)
	v_mfma_f32_16x16x32_bf16 v[158:161], v[178:181], v[130:133], v[158:161]
	v_mfma_f32_16x16x32_bf16 v[154:157], v[170:173], v[130:133], v[154:157]
	v_mfma_f32_16x16x32_bf16 v[150:153], v[166:169], v[130:133], v[150:153]
	v_mfma_f32_16x16x32_bf16 v[146:149], v[162:165], v[130:133], v[146:149]
	v_mfma_f32_16x16x32_bf16 v[142:145], v[178:181], v[126:129], v[142:145]
	v_mfma_f32_16x16x32_bf16 v[138:141], v[170:173], v[126:129], v[138:141]
	v_mfma_f32_16x16x32_bf16 v[134:137], v[166:169], v[126:129], v[134:137]
	v_mfma_f32_16x16x32_bf16 v[114:117], v[162:165], v[126:129], v[114:117]
	v_mfma_f32_16x16x32_bf16 v[110:113], v[178:181], v[122:125], v[110:113]
	v_mfma_f32_16x16x32_bf16 v[106:109], v[170:173], v[122:125], v[106:109]
	v_mfma_f32_16x16x32_bf16 v[102:105], v[166:169], v[122:125], v[102:105]
	v_mfma_f32_16x16x32_bf16 v[98:101], v[162:165], v[122:125], v[98:101]
	v_mfma_f32_16x16x32_bf16 v[94:97], v[178:181], v[118:121], v[94:97]
	v_mfma_f32_16x16x32_bf16 v[90:93], v[170:173], v[118:121], v[90:93]
	v_mfma_f32_16x16x32_bf16 v[74:77], v[166:169], v[118:121], v[74:77]
	v_mfma_f32_16x16x32_bf16 v[66:69], v[162:165], v[118:121], v[66:69]
	s_cbranch_vccnz .LBB0_1170
	s_min_u32 s46, s48, 2
	s_cmp_lg_u32 s46, 2
	s_mov_b64 s[46:47], -1
	s_cbranch_scc0 .LBB0_1168
	s_cmp_lg_u32 s49, 28
	s_cbranch_scc0 .LBB0_1165
	s_waitcnt vmcnt(0)
	s_mov_b64 s[46:47], 0

.LBB0_1170:
	s_cmp_gt_u32 s49, 26
	s_barrier
.LBB0_1172:
	s_add_i32 s46, s50, 1
	s_cmp_lg_u32 s50, 3
	s_cselect_b32 s46, s46, 0
	s_andn2_b64 vcc, exec, s[44:45]
	s_cbranch_vccnz .LBB0_1154
	s_lshl_b32 s44, s46, 15
	v_or_b32_e32 v86, s44, v243
	ds_read_b128 v[70:73], v86 offset:0
	ds_read_b128 v[78:81], v86 offset:1024
	ds_read_b128 v[82:85], v86 offset:2048
	ds_read_b128 v[86:89], v86 offset:3072
	v_add_u32_e32 v118, s44, v240
	ds_read_b128 v[130:133], v118 offset:0
	ds_read_b128 v[126:129], v118 offset:1024
	ds_read_b128 v[122:125], v118 offset:2048
	ds_read_b128 v[118:121], v118 offset:3072
	s_branch .LBB0_1154

.LBB0_1253:
	s_or_b64 exec, exec, s[40:41]
	s_waitcnt lgkmcnt(0)
	s_barrier
	ds_read_b32 v0, v230
	s_waitcnt lgkmcnt(0)
	v_cmp_gt_i32_e32 vcc, 0, v0
	v_readfirstlane_b32 s40, v0
	s_cbranch_vccnz .LBB0_1285
	v_mov_b32_e32 v126, v195
	s_movk_i32 s41, 0x78
	v_lshrrev_b32_e32 v1, 1, v126
	v_and_b32_e32 v1, 6, v1
	v_bfe_u32 v125, v126, 4, 2
	v_lshrrev_b32_e64 v1, v1, s41
	v_bitop3_b32 v1, v1, v125, 3 bitop3:0x6c
	v_lshlrev_b32_e32 v0, 1, v125
	v_lshlrev_b32_e32 v11, 4, v1
	v_ashrrev_i32_e32 v1, 1, v126
	s_lshl_b32 s34, s40, 2
	v_ashrrev_i32_e32 v6, 6, v126
	v_lshrrev_b32_e64 v32, v0, s41
	v_and_b32_e32 v127, 15, v126
	v_and_b32_e32 v128, 0xffffffc0, v1
	s_and_b32 s43, s34, 0x7fffff00
	v_xor_b32_e32 v0, v32, v126
	v_bfe_u32 v10, v126, 2, 4
	v_or_b32_e32 v1, v128, v127
	v_lshlrev_b32_e32 v26, 4, v6
	v_lshl_or_b32 v129, v1, 6, v11
	v_lshlrev_b32_e32 v1, 6, v126
	v_lshlrev_b32_e32 v0, 4, v0
	v_ashrrev_i32_e32 v27, 31, v26
	v_or_b32_e32 v30, s43, v10
	v_mov_b32_e32 v31, v17
	v_and_b32_e32 v12, 0x13c0, v1
	v_and_b32_e32 v0, 48, v0
	v_mov_b32_e32 v1, v17
	v_lshlrev_b32_e32 v130, 10, v6
	v_lshl_add_u64 v[4:5], v[30:31], 0, v[26:27]
	v_lshl_add_u64 v[2:3], s[30:31], 0, v[0:1]
	v_lshlrev_b64 v[4:5], 6, v[4:5]
	v_readfirstlane_b32 s41, v130
	v_lshl_add_u64 v[4:5], v[2:3], 0, v[4:5]
	s_mov_b32 m0, s41
	v_add_u32_e32 v8, 8, v6
	global_load_lds_dwordx4 v[4:5], off
	v_lshlrev_b32_e32 v4, 4, v8
	v_ashrrev_i32_e32 v5, 31, v4
	v_lshl_add_u64 v[6:7], v[30:31], 0, v[4:5]
	v_lshlrev_b32_e32 v131, 10, v8
	s_lshl_b32 s34, s40, 7
	v_lshlrev_b64 v[6:7], 6, v[6:7]
	v_readfirstlane_b32 s41, v131
	s_and_b32 s34, s34, 0x1f80
	v_or_b32_e32 v28, v26, v10
	v_mov_b32_e32 v29, v27
	v_lshl_add_u64 v[6:7], v[2:3], 0, v[6:7]
	s_mov_b32 m0, s41
	v_add_u32_e32 v8, 0x4000, v130
	global_load_lds_dwordx4 v[6:7], off
	v_lshl_add_u64 v[6:7], v[28:29], 0, s[34:35]
	v_lshl_add_u64 v[0:1], s[56:57], 0, v[0:1]
	v_lshlrev_b64 v[6:7], 6, v[6:7]
	v_readfirstlane_b32 s41, v8
	v_lshl_add_u64 v[6:7], v[0:1], 0, v[6:7]
	s_mov_b32 m0, s41
	s_add_i32 s41, s43, 0x9000
	global_load_lds_dwordx4 v[6:7], off
	v_or_b32_e32 v6, s41, v10
	v_mov_b32_e32 v7, v17
	v_lshl_add_u64 v[8:9], v[6:7], 0, v[26:27]
	v_add_u32_e32 v13, 0x6000, v130
	v_lshlrev_b64 v[8:9], 6, v[8:9]
	v_readfirstlane_b32 s41, v13
	v_lshl_add_u64 v[8:9], v[2:3], 0, v[8:9]
	s_mov_b32 m0, s41
	v_lshl_add_u64 v[6:7], v[6:7], 0, v[4:5]
	global_load_lds_dwordx4 v[8:9], off
	v_add_u32_e32 v8, 0x6000, v131
	v_lshlrev_b64 v[6:7], 6, v[6:7]
	v_readfirstlane_b32 s41, v8
	v_lshl_add_u64 v[6:7], v[2:3], 0, v[6:7]
	s_mov_b32 m0, s41
	s_add_i32 s44, s34, 0x400
	s_mov_b32 s45, s35
	global_load_lds_dwordx4 v[6:7], off
	v_lshl_add_u64 v[6:7], v[28:29], 0, s[44:45]
	v_add_u32_e32 v8, 0xa000, v130
	v_lshlrev_b64 v[6:7], 6, v[6:7]
	v_readfirstlane_b32 s41, v8
	v_lshl_add_u64 v[6:7], v[0:1], 0, v[6:7]
	s_mov_b32 m0, s41
	s_add_i32 s41, s43, 0x12000
	global_load_lds_dwordx4 v[6:7], off
	v_or_b32_e32 v6, s41, v10
	v_mov_b32_e32 v7, v17
	v_lshl_add_u64 v[8:9], v[6:7], 0, v[26:27]
	v_add_u32_e32 v13, 0xc000, v130
	v_lshlrev_b64 v[8:9], 6, v[8:9]
	v_readfirstlane_b32 s41, v13
	v_lshl_add_u64 v[8:9], v[2:3], 0, v[8:9]
	s_mov_b32 m0, s41
	v_lshl_add_u64 v[6:7], v[6:7], 0, v[4:5]
	global_load_lds_dwordx4 v[8:9], off
	v_add_u32_e32 v8, 0xc000, v131
	v_lshlrev_b64 v[6:7], 6, v[6:7]
	v_readfirstlane_b32 s41, v8
	v_lshl_add_u64 v[6:7], v[2:3], 0, v[6:7]
	s_mov_b32 m0, s41
	s_add_i32 s44, s34, 0x800
	global_load_lds_dwordx4 v[6:7], off
	v_lshl_add_u64 v[6:7], v[28:29], 0, s[44:45]
	v_add_u32_e32 v8, 0x10000, v130
	v_lshlrev_b64 v[6:7], 6, v[6:7]
	v_readfirstlane_b32 s41, v8
	v_lshl_add_u64 v[6:7], v[0:1], 0, v[6:7]
	s_mov_b32 m0, s41
	s_add_i32 s41, s43, 0x1b000
	global_load_lds_dwordx4 v[6:7], off
	v_or_b32_e32 v6, s41, v10
	v_mov_b32_e32 v7, v17
	v_lshl_add_u64 v[8:9], v[6:7], 0, v[26:27]
	v_add_u32_e32 v13, 0x12000, v130
	v_lshlrev_b64 v[8:9], 6, v[8:9]
	v_readfirstlane_b32 s41, v13
	v_lshl_add_u64 v[8:9], v[2:3], 0, v[8:9]
	s_mov_b32 m0, s41
	v_lshl_add_u64 v[6:7], v[6:7], 0, v[4:5]
	global_load_lds_dwordx4 v[8:9], off
	v_add_u32_e32 v8, 0x12000, v131
	v_lshlrev_b64 v[6:7], 6, v[6:7]
	v_readfirstlane_b32 s41, v8
	v_lshl_add_u64 v[6:7], v[2:3], 0, v[6:7]
	s_mov_b32 m0, s41
	s_add_i32 s44, s34, 0xc00
	global_load_lds_dwordx4 v[6:7], off
	v_lshl_add_u64 v[6:7], v[28:29], 0, s[44:45]
	v_add_u32_e32 v8, 0x16000, v130
	v_lshlrev_b64 v[6:7], 6, v[6:7]
	v_readfirstlane_b32 s41, v8
	v_lshl_add_u64 v[6:7], v[0:1], 0, v[6:7]
	s_mov_b32 m0, s41
	s_add_i32 s41, s43, 0x24000
	global_load_lds_dwordx4 v[6:7], off
	v_or_b32_e32 v6, s41, v10
	v_mov_b32_e32 v7, v17
	v_lshl_add_u64 v[8:9], v[6:7], 0, v[26:27]
	v_add_u32_e32 v13, 0x18000, v130
	v_lshlrev_b64 v[8:9], 6, v[8:9]
	v_readfirstlane_b32 s41, v13
	v_lshl_add_u64 v[8:9], v[2:3], 0, v[8:9]
	s_mov_b32 m0, s41
	v_lshl_add_u64 v[6:7], v[6:7], 0, v[4:5]
	global_load_lds_dwordx4 v[8:9], off
	v_add_u32_e32 v8, 0x18000, v131
	v_lshlrev_b64 v[6:7], 6, v[6:7]
	v_readfirstlane_b32 s41, v8
	v_lshl_add_u64 v[6:7], v[2:3], 0, v[6:7]
	s_mov_b32 m0, s41
	s_add_i32 s44, s34, 0x1000
	global_load_lds_dwordx4 v[6:7], off
	v_lshl_add_u64 v[6:7], v[28:29], 0, s[44:45]
	v_add_u32_e32 v8, 0x1c000, v130
	v_lshlrev_b64 v[6:7], 6, v[6:7]
	v_readfirstlane_b32 s41, v8
	v_lshl_add_u64 v[6:7], v[0:1], 0, v[6:7]
	s_mov_b32 m0, s41
	s_add_i32 s41, s43, 0x2d000
	global_load_lds_dwordx4 v[6:7], off
	v_or_b32_e32 v6, s41, v10
	v_mov_b32_e32 v7, v17
	v_lshl_add_u64 v[8:9], v[6:7], 0, v[26:27]
	v_lshl_add_u64 v[4:5], v[6:7], 0, v[4:5]
	v_lshlrev_b64 v[8:9], 6, v[8:9]
	v_add_u32_e32 v10, 0x1e000, v130
	v_lshlrev_b64 v[4:5], 6, v[4:5]
	v_lshl_add_u64 v[8:9], v[2:3], 0, v[8:9]
	v_readfirstlane_b32 s41, v10
	v_lshl_add_u64 v[2:3], v[2:3], 0, v[4:5]
	v_add_u32_e32 v4, 0x1e000, v131
	s_mov_b32 m0, s41
	v_readfirstlane_b32 s41, v4
	global_load_lds_dwordx4 v[8:9], off
	s_mov_b32 m0, s41
	s_add_i32 s44, s34, 0x1400
	global_load_lds_dwordx4 v[2:3], off
	v_lshl_add_u64 v[2:3], v[28:29], 0, s[44:45]
	v_lshlrev_b64 v[2:3], 6, v[2:3]
	v_lshl_add_u64 v[0:1], v[0:1], 0, v[2:3]
	v_add_u32_e32 v2, 0x22000, v130
	s_and_b32 s40, s40, 63
	v_readfirstlane_b32 s41, v2
	s_mov_b32 m0, s41
	s_movk_i32 s41, 0x4000
	global_load_lds_dwordx4 v[0:1], off
	s_lshl_b32 s40, s40, 13
	v_readlane_b32 s44, v252, 19
	v_or3_b32 v132, v12, v11, s41
	s_waitcnt vmcnt(15)
	s_barrier
	ds_read_b128 v[0:3], v132 offset:0
	v_readlane_b32 s45, v252, 20
	s_add_u32 s40, s44, s40
	ds_read_b128 v[4:7], v132 offset:1024
	v_lshlrev_b64 v[28:29], 6, v[28:29]
	s_addc_u32 s41, s45, 0
	ds_read_b128 v[8:11], v132 offset:2048
	v_lshl_add_u64 v[116:117], s[40:41], 0, v[28:29]
	v_add_u32_e32 v28, 0x3f000, v30
	v_mov_b32_e32 v29, v17
	ds_read_b128 v[12:15], v132 offset:3072
	v_lshl_add_u64 v[28:29], v[26:27], 0, v[28:29]
	ds_read_b128 v[22:25], v129 offset:0
	v_lshlrev_b64 v[28:29], 6, v[28:29]
	ds_read_b128 v[18:21], v129 offset:1024
	v_lshl_add_u64 v[118:119], s[44:45], 0, v[28:29]
	v_add_u32_e32 v28, 0x36000, v30
	v_mov_b32_e32 v29, v17
	s_waitcnt lgkmcnt(0)
	v_lshl_add_u64 v[26:27], v[26:27], 0, v[28:29]
	v_bitop3_b32 v31, v32, 3, v126 bitop3:0x48
	v_lshlrev_b64 v[26:27], 6, v[26:27]
	v_mov_b32_e32 v58, 0
	v_lshlrev_b32_e32 v114, 4, v31
	v_mov_b32_e32 v115, v17
	v_lshl_add_u64 v[120:121], s[44:45], 0, v[26:27]
	s_mov_b32 s46, 0
	s_movk_i32 s52, 0x7d
	s_mov_b32 s53, 0
	v_mov_b32_e32 v59, v58
	v_mov_b32_e32 v60, v58
	v_mov_b32_e32 v61, v58
	v_mov_b32_e32 v78, v58
	v_mov_b32_e32 v79, v58
	v_mov_b32_e32 v80, v58
	v_mov_b32_e32 v81, v58
	v_mov_b32_e32 v30, v58
	v_mov_b32_e32 v31, v58
	v_mov_b32_e32 v32, v58
	v_mov_b32_e32 v33, v58
	v_mov_b32_e32 v26, v58
	v_mov_b32_e32 v27, v58
	v_mov_b32_e32 v28, v58
	v_mov_b32_e32 v29, v58
	v_mov_b32_e32 v42, v58
	v_mov_b32_e32 v43, v58
	v_mov_b32_e32 v44, v58
	v_mov_b32_e32 v45, v58
	v_mov_b32_e32 v50, v58
	v_mov_b32_e32 v51, v58
	v_mov_b32_e32 v52, v58
	v_mov_b32_e32 v53, v58
	v_mov_b32_e32 v62, v58
	v_mov_b32_e32 v63, v58
	v_mov_b32_e32 v64, v58
	v_mov_b32_e32 v65, v58
	v_mov_b32_e32 v70, v58
	v_mov_b32_e32 v71, v58
	v_mov_b32_e32 v72, v58
	v_mov_b32_e32 v73, v58
	v_mov_b32_e32 v34, v58
	v_mov_b32_e32 v35, v58
	v_mov_b32_e32 v36, v58
	v_mov_b32_e32 v37, v58
	v_mov_b32_e32 v38, v58
	v_mov_b32_e32 v39, v58
	v_mov_b32_e32 v40, v58
	v_mov_b32_e32 v41, v58
	v_mov_b32_e32 v46, v58
	v_mov_b32_e32 v47, v58
	v_mov_b32_e32 v48, v58
	v_mov_b32_e32 v49, v58
	v_mov_b32_e32 v54, v58
	v_mov_b32_e32 v55, v58
	v_mov_b32_e32 v56, v58
	v_mov_b32_e32 v57, v58
	v_mov_b32_e32 v66, v58
	v_mov_b32_e32 v67, v58
	v_mov_b32_e32 v68, v58
	v_mov_b32_e32 v69, v58
	v_mov_b32_e32 v74, v58
	v_mov_b32_e32 v75, v58
	v_mov_b32_e32 v76, v58
	v_mov_b32_e32 v77, v58
	v_mov_b32_e32 v82, v58
	v_mov_b32_e32 v83, v58
	v_mov_b32_e32 v84, v58
	v_mov_b32_e32 v85, v58
	v_mov_b32_e32 v86, v58
	v_mov_b32_e32 v87, v58
	v_mov_b32_e32 v88, v58
	v_mov_b32_e32 v89, v58
	v_readfirstlane_b32 s100, v130
	v_readfirstlane_b32 s101, v131
	s_branch .LBB0_1256
.LBB0_1255:
	v_mfma_f32_16x16x32_bf16 v[70:73], v[106:109], v[110:113], v[70:73]
	s_cmpk_gt_u32 s53, 0x78
	s_cbranch_scc1 .Ldma_m2b_0
	s_add_u32 m0, s55, s100
	v_lshl_add_u64 v[244:245], v[118:119], 0, v[114:115]
	v_lshl_add_u64 v[246:247], v[244:245], 0, s[8:9]
	global_load_lds_dwordx4 v[246:247], off
.Ldma_m2b_0:
	s_cmpk_gt_u32 s53, 0x78
	s_cbranch_scc1 .Ldma_m2b_1
	s_add_u32 m0, s55, s101
	s_mov_b64 s[98:99], 0xa923000
	v_lshl_add_u64 v[246:247], v[244:245], 0, s[98:99]
	global_load_lds_dwordx4 v[246:247], off
.Ldma_m2b_1:
	s_waitcnt lgkmcnt(0)
	s_mov_b64 s[44:45], 0x20000
	s_add_i32 s53, s53, 2
	v_mfma_f32_16x16x32_bf16 v[62:65], v[102:105], v[110:113], v[62:65]
	s_cmpk_gt_u32 s53, 0x7a
	s_cbranch_scc1 .Ldma_m2b_2
	s_add_u32 m0, s55, s100
	s_addk_i32 m0, 0x4000
	s_mov_b64 s[98:99], 0x10b0000
	v_lshl_add_u64 v[246:247], v[122:123], 0, s[98:99]
	global_load_lds_dwordx4 v[246:247], off
.Ldma_m2b_2:
	v_lshl_add_u64 v[116:117], v[116:117], 0, s[44:45]
	v_lshl_add_u64 v[118:119], v[118:119], 0, s[36:37]
	s_add_i32 s52, s52, -2
	v_mfma_f32_16x16x32_bf16 v[50:53], v[94:97], v[110:113], v[50:53]
	v_lshl_add_u64 v[120:121], v[120:121], 0, s[36:37]
	s_andn2_b64 vcc, exec, s[40:41]
	v_mfma_f32_16x16x32_bf16 v[42:45], v[90:93], v[110:113], v[42:45]
	v_mfma_f32_16x16x32_bf16 v[26:29], v[106:109], v[98:101], v[26:29]
	v_mfma_f32_16x16x32_bf16 v[30:33], v[102:105], v[98:101], v[30:33]
	v_mfma_f32_16x16x32_bf16 v[78:81], v[94:97], v[98:101], v[78:81]
	v_mfma_f32_16x16x32_bf16 v[58:61], v[90:93], v[98:101], v[58:61]
	s_cbranch_vccz .LBB0_1242

.LBB0_1266:
	s_add_i32 s40, s46, 1
	s_cmp_lg_u32 s46, 5
	s_cselect_b32 s54, s40, 0
	s_mul_i32 s55, s54, 0x6000
	v_add_u32_e32 v18, s55, v132
	ds_read_b128 v[106:109], v18 offset:0
	ds_read_b128 v[102:105], v18 offset:1024
	ds_read_b128 v[94:97], v18 offset:2048
	ds_read_b128 v[90:93], v18 offset:3072
	v_mfma_f32_16x16x32_bf16 v[70:73], v[0:3], v[22:25], v[70:73]
	v_add_u32_e32 v133, s55, v129
	s_cmpk_lt_u32 s53, 0x7e
	s_cselect_b64 s[44:45], -1, 0
	v_mfma_f32_16x16x32_bf16 v[62:65], v[4:7], v[22:25], v[62:65]
	s_cmpk_gt_u32 s53, 0x7d
	s_cselect_b64 s[40:41], -1, 0
	s_and_b64 vcc, exec, s[40:41]
	v_mfma_f32_16x16x32_bf16 v[50:53], v[8:11], v[22:25], v[50:53]
	s_cmpk_gt_u32 s53, 0x79
	s_cbranch_scc1 .Ldma_m2a_0
	s_mul_i32 m0, s46, 0x6000
	s_add_u32 m0, m0, s100
	v_lshl_add_u64 v[244:245], v[120:121], 0, v[114:115]
	v_lshl_add_u64 v[246:247], v[244:245], 0, s[8:9]
	global_load_lds_dwordx4 v[246:247], off
.Ldma_m2a_0:
	v_mfma_f32_16x16x32_bf16 v[42:45], v[12:15], v[22:25], v[42:45]
	ds_read_b128 v[22:25], v133 offset:0
	ds_read_b128 v[18:21], v133 offset:1024
	s_cmpk_gt_u32 s53, 0x79
	s_cbranch_scc1 .Ldma_m2a_1
	s_mul_i32 m0, s46, 0x6000
	s_add_u32 m0, m0, s101
	s_mov_b64 s[98:99], 0xa923000
	v_lshl_add_u64 v[246:247], v[244:245], 0, s[98:99]
	global_load_lds_dwordx4 v[246:247], off
.Ldma_m2a_1:
	s_cmpk_gt_u32 s53, 0x79
	s_cbranch_scc1 .Ldma_m2a_2
	s_mul_i32 m0, s46, 0x6000
	s_add_u32 m0, m0, s100
	s_addk_i32 m0, 0x4000
	s_mov_b64 s[98:99], 0x10a0000
	v_lshl_add_u64 v[246:247], v[122:123], 0, s[98:99]
	global_load_lds_dwordx4 v[246:247], off
.Ldma_m2a_2:
	s_nop 0
	s_waitcnt lgkmcnt(0)
	ds_read_b128 v[110:113], v133 offset:2048
	v_mfma_f32_16x16x32_bf16 v[26:29], v[0:3], v[98:101], v[26:29]
	v_mfma_f32_16x16x32_bf16 v[30:33], v[4:7], v[98:101], v[30:33]
	v_mfma_f32_16x16x32_bf16 v[78:81], v[8:11], v[98:101], v[78:81]
	v_mfma_f32_16x16x32_bf16 v[58:61], v[12:15], v[98:101], v[58:61]
	ds_read_b128 v[98:101], v133 offset:3072
	s_nop 0
	s_waitcnt lgkmcnt(0)
	v_mfma_f32_16x16x32_bf16 v[86:89], v[106:109], v[22:25], v[86:89]
	v_mfma_f32_16x16x32_bf16 v[82:85], v[102:105], v[22:25], v[82:85]
	v_mfma_f32_16x16x32_bf16 v[74:77], v[94:97], v[22:25], v[74:77]
	v_mfma_f32_16x16x32_bf16 v[66:69], v[90:93], v[22:25], v[66:69]
	v_mfma_f32_16x16x32_bf16 v[54:57], v[106:109], v[18:21], v[54:57]
	v_mfma_f32_16x16x32_bf16 v[46:49], v[102:105], v[18:21], v[46:49]
	v_mfma_f32_16x16x32_bf16 v[38:41], v[94:97], v[18:21], v[38:41]
	v_mfma_f32_16x16x32_bf16 v[34:37], v[90:93], v[18:21], v[34:37]
	s_cbranch_vccnz .LBB0_1276
	s_min_u32 s46, s52, 4
	s_cmp_lg_u32 s46, 4
	s_mov_b64 s[46:47], -1
	s_cbranch_scc0 .LBB0_1274
	s_mov_b64 s[50:51], -1
	s_mov_b64 s[46:47], 0
	s_cmpk_lt_i32 s53, 0x7c
	s_mov_b64 s[48:49], 0
	s_cbranch_scc0 .LBB0_1280
	s_and_b64 vcc, exec, s[50:51]
	s_cbranch_vccnz .LBB0_1283

.LBB0_1276:
	s_cmpk_gt_u32 s53, 0x78
	s_barrier
.LBB0_1278:
	s_add_i32 s46, s54, 1
	s_cmp_lg_u32 s54, 5
	s_cselect_b32 s46, s46, 0
	s_andn2_b64 vcc, exec, s[44:45]
	s_cbranch_vccnz .LBB0_1255
	s_mul_i32 s44, s46, 0x6000
	v_add_u32_e32 v12, s44, v132
	ds_read_b128 v[0:3], v12 offset:0
	ds_read_b128 v[4:7], v12 offset:1024
	ds_read_b128 v[8:11], v12 offset:2048
	ds_read_b128 v[12:15], v12 offset:3072
	v_add_u32_e32 v18, s44, v129
	ds_read_b128 v[22:25], v18 offset:0
	ds_read_b128 v[18:21], v18 offset:1024
	s_branch .LBB0_1255

.LBB0_1386:
	v_mov_b32_e32 v0, v217
	v_mov_b32_e32 v2, v217
	v_ashrrev_i32_e32 v0, 4, v0
	v_and_b32_e32 v4, -4, v0
	v_add3_u32 v58, v74, s34, v4
	v_ashrrev_i32_e32 v59, 31, v58
	v_lshlrev_b32_e32 v77, 3, v2
	v_lshlrev_b64 v[0:1], 11, v[58:59]
	v_and_b32_e32 v76, 0x1f8, v77
	v_lshl_add_u64 v[0:1], s[6:7], 0, v[0:1]
	v_lshlrev_b32_e32 v2, 1, v76
	v_mov_b32_e32 v3, v17
	v_lshl_add_u64 v[0:1], v[0:1], 0, v[2:3]
	global_load_dwordx4 v[54:57], v[0:1], off
	global_load_dwordx4 v[50:53], v[0:1], off offset:1024
	v_cmp_lt_i32_e32 vcc, v221, v220
	v_lshlrev_b32_e32 v16, 2, v76
	v_mov_b64_e32 v[18:19], s[28:29]
	v_cndmask_b32_e32 v0, v218, v221, vcc
	v_lshlrev_b32_e32 v78, 2, v0
	v_add3_u32 v0, v4, v74, s86
	v_lshrrev_b32_e32 v20, 12, v0
	v_add_u32_e32 v22, 1, v20
	v_lshlrev_b64 v[20:21], 12, v[58:59]
	v_cmp_lt_i32_e32 vcc, s2, v58
	v_lshl_add_u64 v[20:21], s[18:19], 0, v[20:21]
	v_lshl_add_u64 v[62:63], v[20:21], 0, v[16:17]
	v_cndmask_b32_e32 v79, 0, v22, vcc
	v_add_u32_e32 v20, s25, v79
	s_mov_b64 s[56:57], 0x5000
	v_or_b32_e32 v75, 0x200, v76
	v_mad_u64_u32 v[34:35], s[58:59], v20, s24, v[18:19]
	v_mov_b32_e32 v61, v17
	v_lshlrev_b32_e32 v60, 2, v75
	v_lshl_add_u64 v[34:35], v[34:35], 0, s[56:57]
	global_load_dwordx4 v[0:3], v16, s[10:11] offset:16
	global_load_dwordx4 v[4:7], v16, s[10:11]
	global_load_dwordx4 v[8:11], v16, s[10:11] offset:2064
	global_load_dwordx4 v[12:15], v16, s[10:11] offset:2048
	v_lshl_add_u64 v[36:37], v[34:35], 0, v[16:17]
	v_lshl_add_u64 v[42:43], v[34:35], 0, v[60:61]
	global_load_dwordx4 v[22:25], v[62:63], off offset:16
	global_load_dwordx4 v[30:33], v[62:63], off
	global_load_dwordx4 v[18:21], v[62:63], off offset:2064
	global_load_dwordx4 v[26:29], v[62:63], off offset:2048
	global_load_dwordx4 v[38:41], v[36:37], off offset:16
	global_load_dwordx4 v[46:49], v[36:37], off
	s_nop 0
	global_load_dwordx4 v[34:37], v[42:43], off offset:16
	s_nop 0
	global_load_dwordx4 v[42:45], v[42:43], off
	v_cmp_lt_i32_e32 vcc, v222, v220
	s_waitcnt vmcnt(13)
	v_and_b32_e32 v65, 0xffff0000, v54
	v_lshlrev_b32_e32 v64, 16, v54
	v_and_b32_e32 v67, 0xffff0000, v55
	v_lshlrev_b32_e32 v66, 16, v55
	v_and_b32_e32 v55, 0xffff0000, v56
	v_lshlrev_b32_e32 v54, 16, v56
	v_and_b32_e32 v69, 0xffff0000, v57
	v_lshlrev_b32_e32 v68, 16, v57
	s_waitcnt vmcnt(12)
	v_and_b32_e32 v57, 0xffff0000, v50
	v_lshlrev_b32_e32 v56, 16, v50
	v_and_b32_e32 v71, 0xffff0000, v51
	v_lshlrev_b32_e32 v70, 16, v51
	v_and_b32_e32 v51, 0xffff0000, v52
	v_lshlrev_b32_e32 v50, 16, v52
	v_and_b32_e32 v73, 0xffff0000, v53
	v_lshlrev_b32_e32 v72, 16, v53
	v_pk_mul_f32 v[52:53], v[64:65], v[64:65]
	v_pk_mul_f32 v[80:81], v[66:67], v[66:67]
	v_add_f32_e32 v52, v52, v53
	v_add_f32_e32 v52, v80, v52
	v_pk_mul_f32 v[82:83], v[54:55], v[54:55]
	v_add_f32_e32 v52, v81, v52
	v_add_f32_e32 v52, v82, v52
	v_pk_mul_f32 v[84:85], v[68:69], v[68:69]
	v_add_f32_e32 v52, v83, v52
	v_add_f32_e32 v52, v84, v52
	v_pk_mul_f32 v[86:87], v[56:57], v[56:57]
	v_add_f32_e32 v52, v85, v52
	v_add_f32_e32 v52, v86, v52
	v_pk_mul_f32 v[88:89], v[70:71], v[70:71]
	v_add_f32_e32 v52, v87, v52
	v_add_f32_e32 v52, v88, v52
	v_pk_mul_f32 v[90:91], v[50:51], v[50:51]
	v_add_f32_e32 v52, v89, v52
	v_add_f32_e32 v52, v90, v52
	v_pk_mul_f32 v[92:93], v[72:73], v[72:73]
	v_add_f32_e32 v52, v91, v52
	v_add_f32_e32 v52, v92, v52
	v_add_f32_e32 v53, v93, v52
	v_mov_b32_e32 v83, v53
	s_waitcnt lgkmcnt(0)
	s_nop 1
	v_add_f32_dpp v83, v83, v83 quad_perm:[1,0,3,2] row_mask:0xf bank_mask:0xf
	s_nop 1
	v_add_f32_dpp v83, v83, v83 quad_perm:[2,3,0,1] row_mask:0xf bank_mask:0xf
	s_nop 1
	v_add_f32_dpp v83, v83, v83 row_half_mirror row_mask:0xf bank_mask:0xf
	s_nop 1
	v_add_f32_dpp v83, v83, v83 row_mirror row_mask:0xf bank_mask:0xf
	v_mov_b32_e32 v84, v83
	s_nop 1
	v_permlane16_swap_b32_e32 v83, v84
	v_add_f32_e32 v83, v83, v84
	v_mov_b32_e32 v84, v83
	s_nop 1
	v_permlane32_swap_b32_e32 v83, v84
	v_add_f32_e32 v83, v83, v84
	v_fmamk_f32 v83, v83, 0x3a800000, v231
	v_mul_f32_e32 v84, 0x4b800000, v83
	v_cmp_gt_f32_e32 vcc, s3, v83
	s_nop 1
	v_cndmask_b32_e32 v83, v83, v84, vcc
	v_rsq_f32_e32 v83, v83
	s_nop 0
	v_mul_f32_e32 v84, 0x45800000, v83
	v_cndmask_b32_e32 v84, v83, v84, vcc
	v_pk_mul_f32 v[64:65], v[84:85], v[64:65] op_sel_hi:[0,1]
	v_pk_mul_f32 v[66:67], v[84:85], v[66:67] op_sel_hi:[0,1]
	v_pk_mul_f32 v[54:55], v[84:85], v[54:55] op_sel_hi:[0,1]
	v_pk_mul_f32 v[68:69], v[84:85], v[68:69] op_sel_hi:[0,1]
	v_pk_mul_f32 v[56:57], v[84:85], v[56:57] op_sel_hi:[0,1]
	v_pk_mul_f32 v[70:71], v[84:85], v[70:71] op_sel_hi:[0,1]
	v_pk_mul_f32 v[50:51], v[84:85], v[50:51] op_sel_hi:[0,1]
	v_pk_mul_f32 v[72:73], v[84:85], v[72:73] op_sel_hi:[0,1]
	s_waitcnt vmcnt(10)
	v_pk_mul_f32 v[4:5], v[4:5], v[64:65]
	v_pk_mul_f32 v[6:7], v[6:7], v[66:67]
	v_pk_mul_f32 v[0:1], v[0:1], v[54:55]
	v_pk_mul_f32 v[2:3], v[2:3], v[68:69]
	s_waitcnt vmcnt(8)
	v_pk_mul_f32 v[54:55], v[12:13], v[56:57]
	v_pk_mul_f32 v[56:57], v[14:15], v[70:71]
	v_pk_mul_f32 v[50:51], v[50:51], v[8:9]
	v_pk_mul_f32 v[64:65], v[72:73], v[10:11]
	s_waitcnt vmcnt(2)
	v_pk_fma_f32 v[12:13], v[46:47], v[4:5], v[30:31]
	v_pk_fma_f32 v[14:15], v[48:49], v[6:7], v[32:33]
	v_pk_fma_f32 v[8:9], v[38:39], v[0:1], v[22:23]
	v_pk_fma_f32 v[10:11], v[40:41], v[2:3], v[24:25]
	s_waitcnt vmcnt(0)
	v_pk_fma_f32 v[4:5], v[42:43], v[54:55], v[26:27]
	v_pk_fma_f32 v[6:7], v[44:45], v[56:57], v[28:29]
	v_pk_fma_f32 v[0:1], v[34:35], v[50:51], v[18:19]
	v_pk_fma_f32 v[2:3], v[36:37], v[64:65], v[20:21]
	s_andn2_b64 vcc, exec, s[0:1]
	global_store_dwordx4 v[62:63], v[12:15], off
	global_store_dwordx4 v[62:63], v[8:11], off offset:16
	global_store_dwordx4 v[62:63], v[4:7], off offset:2048
	global_store_dwordx4 v[62:63], v[0:3], off offset:2064
	s_cbranch_vccnz .LBB0_1385
	v_readlane_b32 s56, v254, 45
	s_mul_i32 s56, s56, 9
	v_readlane_b32 s57, v254, 46
	v_add_u32_e32 v20, s56, v79
	v_mov_b64_e32 v[18:19], s[28:29]
	v_mad_u64_u32 v[20:21], s[56:57], v20, s24, v[18:19]
	v_pk_mul_f32 v[18:19], v[12:13], v[12:13]
	v_pk_mul_f32 v[22:23], v[14:15], v[14:15]
	v_add_f32_e32 v18, v18, v19
	v_add_f32_e32 v18, v22, v18
	v_pk_mul_f32 v[24:25], v[8:9], v[8:9]
	v_add_f32_e32 v18, v23, v18
	v_add_f32_e32 v18, v24, v18
	v_pk_mul_f32 v[26:27], v[10:11], v[10:11]
	v_add_f32_e32 v18, v25, v18
	v_add_f32_e32 v18, v26, v18
	v_pk_mul_f32 v[28:29], v[4:5], v[4:5]
	v_add_f32_e32 v18, v27, v18
	v_add_f32_e32 v18, v28, v18
	v_pk_mul_f32 v[30:31], v[6:7], v[6:7]
	v_add_f32_e32 v18, v29, v18
	v_add_f32_e32 v18, v30, v18
	v_pk_mul_f32 v[32:33], v[0:1], v[0:1]
	v_add_f32_e32 v18, v31, v18
	v_add_f32_e32 v18, v32, v18
	s_mov_b64 s[56:57], 0x1000
	v_pk_mul_f32 v[34:35], v[2:3], v[2:3]
	v_add_f32_e32 v18, v33, v18
	v_lshl_add_u64 v[22:23], v[20:21], 0, s[56:57]
	v_add_f32_e32 v18, v34, v18
	v_lshl_add_u64 v[36:37], v[22:23], 0, v[16:17]
	v_add_f32_e32 v18, v35, v18
	v_lshl_add_u64 v[20:21], v[20:21], 0, v[16:17]
	global_load_dwordx4 v[24:27], v16, s[52:53] offset:16
	global_load_dwordx4 v[28:31], v16, s[52:53]
	global_load_dwordx4 v[32:35], v[36:37], off offset:16
	s_nop 0
	global_load_dwordx4 v[36:39], v[36:37], off
	s_nop 0
	global_load_dwordx4 v[40:43], v[20:21], off offset:16
	global_load_dwordx4 v[44:47], v[20:21], off
	s_waitcnt lgkmcnt(0)
	s_nop 1
	v_add_f32_dpp v18, v18, v18 quad_perm:[1,0,3,2] row_mask:0xf bank_mask:0xf
	s_nop 1
	v_add_f32_dpp v18, v18, v18 quad_perm:[2,3,0,1] row_mask:0xf bank_mask:0xf
	s_nop 1
	v_add_f32_dpp v18, v18, v18 row_half_mirror row_mask:0xf bank_mask:0xf
	s_nop 1
	v_add_f32_dpp v18, v18, v18 row_mirror row_mask:0xf bank_mask:0xf
	v_mov_b32_e32 v19, v18
	s_nop 1
	v_permlane16_swap_b32_e32 v18, v19
	v_add_f32_e32 v18, v18, v19
	v_mov_b32_e32 v19, v18
	s_nop 1
	v_permlane32_swap_b32_e32 v18, v19
	v_add_f32_e32 v18, v18, v19
	v_fmamk_f32 v18, v18, 0x3a800000, v231
	v_cmp_gt_f32_e32 vcc, s3, v18
	v_mul_f32_e32 v19, 0x4b800000, v18
	s_nop 0
	v_cndmask_b32_e32 v18, v18, v19, vcc
	v_rsq_f32_e32 v18, v18
	s_nop 0
	v_mul_f32_e32 v19, 0x45800000, v18
	v_cndmask_b32_e32 v18, v18, v19, vcc
	v_and_b32_e32 v19, 24, v77
	v_pk_mul_f32 v[12:13], v[12:13], v[18:19] op_sel_hi:[1,0]
	v_pk_mul_f32 v[14:15], v[14:15], v[18:19] op_sel_hi:[1,0]
	v_pk_mul_f32 v[8:9], v[8:9], v[18:19] op_sel_hi:[1,0]
	v_pk_mul_f32 v[4:5], v[4:5], v[18:19] op_sel_hi:[1,0]
	v_pk_mul_f32 v[6:7], v[6:7], v[18:19] op_sel_hi:[1,0]
	v_pk_mul_f32 v[0:1], v[0:1], v[18:19] op_sel_hi:[1,0]
	s_waitcnt vmcnt(5)
	v_pk_mul_f32 v[8:9], v[8:9], v[24:25]
	s_waitcnt vmcnt(4)
	v_pk_mul_f32 v[12:13], v[28:29], v[12:13]
	s_waitcnt vmcnt(2)
	v_pk_add_f32 v[28:29], v[36:37], 1.0 op_sel_hi:[1,0]
	v_pk_mul_f32 v[14:15], v[30:31], v[14:15]
	s_waitcnt vmcnt(0)
	v_pk_fma_f32 v[12:13], v[28:29], v[12:13], v[44:45]
	v_pk_add_f32 v[28:29], v[38:39], 1.0 op_sel_hi:[1,0]
	v_cvt_pk_bf16_f32 v12, v12, v13
	v_pk_fma_f32 v[14:15], v[28:29], v[14:15], v[46:47]
	s_nop 0
	v_cvt_pk_bf16_f32 v13, v14, v15
	v_pk_add_f32 v[14:15], v[32:33], 1.0 op_sel_hi:[1,0]
	s_nop 0
	v_pk_fma_f32 v[8:9], v[8:9], v[14:15], v[40:41]
	s_nop 0
	v_cvt_pk_bf16_f32 v14, v8, v9
	v_pk_mul_f32 v[8:9], v[10:11], v[18:19] op_sel_hi:[1,0]
	v_pk_add_f32 v[10:11], v[34:35], 1.0 op_sel_hi:[1,0]
	v_pk_mul_f32 v[8:9], v[8:9], v[26:27]
	s_nop 0
	v_pk_fma_f32 v[8:9], v[8:9], v[10:11], v[42:43]
	s_nop 0
	v_cvt_pk_bf16_f32 v15, v8, v9
	v_lshrrev_b32_e32 v8, 5, v76
	v_mul_u32_u24_e32 v8, 0x9000, v8
	v_mov_b32_e32 v9, v17
	v_lshl_add_u64 v[8:9], v[8:9], 0, v[58:59]
	v_lshlrev_b64 v[8:9], 6, v[8:9]
	v_lshl_add_u64 v[10:11], s[4:5], 0, v[8:9]
	v_lshlrev_b32_e32 v8, 1, v19
	v_mov_b32_e32 v9, v17
	v_lshl_add_u64 v[10:11], v[10:11], 0, v[8:9]
	global_store_dwordx4 v[10:11], v[12:15], off
	s_nop 1
	v_lshl_add_u64 v[14:15], v[22:23], 0, v[60:61]
	global_load_dwordx4 v[10:13], v16, s[52:53] offset:2064
	global_load_dwordx4 v[22:25], v16, s[52:53] offset:2048
	global_load_dwordx4 v[26:29], v[14:15], off offset:16
	global_load_dwordx4 v[30:33], v[14:15], off
	s_waitcnt vmcnt(3)
	v_pk_mul_f32 v[0:1], v[0:1], v[10:11]
	s_waitcnt vmcnt(2)
	v_pk_mul_f32 v[4:5], v[4:5], v[22:23]
	global_load_dwordx4 v[34:37], v[20:21], off offset:2064
	s_nop 0
	global_load_dwordx4 v[20:23], v[20:21], off offset:2048
	s_waitcnt vmcnt(2)
	v_pk_add_f32 v[14:15], v[30:31], 1.0 op_sel_hi:[1,0]
	v_pk_mul_f32 v[6:7], v[6:7], v[24:25]
	s_waitcnt vmcnt(0)
	v_pk_fma_f32 v[4:5], v[4:5], v[14:15], v[20:21]
	v_pk_add_f32 v[14:15], v[32:33], 1.0 op_sel_hi:[1,0]
	v_cvt_pk_bf16_f32 v4, v4, v5
	v_pk_fma_f32 v[6:7], v[6:7], v[14:15], v[22:23]
	s_nop 0
	v_cvt_pk_bf16_f32 v5, v6, v7
	v_pk_add_f32 v[6:7], v[26:27], 1.0 op_sel_hi:[1,0]
	s_nop 0
	v_pk_fma_f32 v[0:1], v[0:1], v[6:7], v[34:35]
	s_nop 0
	v_cvt_pk_bf16_f32 v6, v0, v1
	v_pk_mul_f32 v[0:1], v[2:3], v[18:19] op_sel_hi:[1,0]
	v_pk_add_f32 v[2:3], v[28:29], 1.0 op_sel_hi:[1,0]
	v_pk_mul_f32 v[0:1], v[0:1], v[12:13]
	s_nop 0
	v_pk_fma_f32 v[0:1], v[0:1], v[2:3], v[36:37]
	s_nop 0
	v_cvt_pk_bf16_f32 v7, v0, v1
	v_lshrrev_b32_e32 v0, 5, v75
	v_mul_u32_u24_e32 v16, 0x9000, v0
	v_lshl_add_u64 v[0:1], v[16:17], 0, v[58:59]
	v_lshlrev_b64 v[0:1], 6, v[0:1]
	v_lshl_add_u64 v[0:1], s[4:5], 0, v[0:1]
	v_lshl_add_u64 v[0:1], v[0:1], 0, v[8:9]
	global_store_dwordx4 v[0:1], v[4:7], off
	s_branch .LBB0_1385

	.amdhsa_kernel _Z21hybrid_dit_megakernel6Params
		.amdhsa_group_segment_fixed_size 147468
		.amdhsa_private_segment_fixed_size 0
		.amdhsa_kernarg_size 552
		.amdhsa_user_sgpr_count 2
		.amdhsa_user_sgpr_dispatch_ptr 0
		.amdhsa_user_sgpr_queue_ptr 0
		.amdhsa_user_sgpr_kernarg_segment_ptr 1
		.amdhsa_user_sgpr_dispatch_id 0
		.amdhsa_user_sgpr_kernarg_preload_length 0
		.amdhsa_user_sgpr_kernarg_preload_offset 0
		.amdhsa_user_sgpr_private_segment_size 0
		.amdhsa_uses_dynamic_stack 0
		.amdhsa_enable_private_segment 0
		.amdhsa_system_sgpr_workgroup_id_x 1
		.amdhsa_system_sgpr_workgroup_id_y 0
		.amdhsa_system_sgpr_workgroup_id_z 0
		.amdhsa_system_sgpr_workgroup_info 0
		.amdhsa_system_vgpr_workitem_id 2
		.amdhsa_next_free_vgpr 256
		.amdhsa_next_free_sgpr 102
		.amdhsa_accum_offset 256
		.amdhsa_reserve_vcc 1
		.amdhsa_float_round_mode_32 0
		.amdhsa_float_round_mode_16_64 0
		.amdhsa_float_denorm_mode_32 3
		.amdhsa_float_denorm_mode_16_64 3
		.amdhsa_dx10_clamp 1
		.amdhsa_ieee_mode 1
		.amdhsa_fp16_overflow 0
		.amdhsa_tg_split 0
		.amdhsa_exception_fp_ieee_invalid_op 0
		.amdhsa_exception_fp_denorm_src 0
		.amdhsa_exception_fp_ieee_div_zero 0
		.amdhsa_exception_fp_ieee_overflow 0
		.amdhsa_exception_fp_ieee_underflow 0
		.amdhsa_exception_fp_ieee_inexact 0
		.amdhsa_exception_int_div_zero 0
	.end_amdhsa_kernel

amdhsa.kernels:
  - .agpr_count:     0
    .args:
      - .offset:         0
        .size:           296
        .value_kind:     by_value
      - .offset:         296
        .size:           4
        .value_kind:     hidden_block_count_x
      - .offset:         300
        .size:           4
        .value_kind:     hidden_block_count_y
      - .offset:         304
        .size:           4
        .value_kind:     hidden_block_count_z
      - .offset:         308
        .size:           2
        .value_kind:     hidden_group_size_x
      - .offset:         310
        .size:           2
        .value_kind:     hidden_group_size_y
      - .offset:         312
        .size:           2
        .value_kind:     hidden_group_size_z
      - .offset:         314
        .size:           2
        .value_kind:     hidden_remainder_x
      - .offset:         316
        .size:           2
        .value_kind:     hidden_remainder_y
      - .offset:         318
        .size:           2
        .value_kind:     hidden_remainder_z
      - .offset:         336
        .size:           8
        .value_kind:     hidden_global_offset_x
      - .offset:         344
        .size:           8
        .value_kind:     hidden_global_offset_y
      - .offset:         352
        .size:           8
        .value_kind:     hidden_global_offset_z
      - .offset:         360
        .size:           2
        .value_kind:     hidden_grid_dims
      - .offset:         384
        .size:           8
        .value_kind:     hidden_multigrid_sync_arg
    .group_segment_fixed_size: 147468
    .kernarg_segment_align: 8
    .kernarg_segment_size: 552
    .language:       OpenCL C
    .language_version:
      - 2
      - 0
    .max_flat_workgroup_size: 512
    .name:           _Z21hybrid_dit_megakernel6Params
    .private_segment_fixed_size: 0
    .sgpr_count:     108
    .sgpr_spill_count: 205
    .symbol:         _Z21hybrid_dit_megakernel6Params.kd
    .uniform_work_group_size: 1
    .uses_dynamic_stack: false
    .vgpr_count:     256
    .vgpr_spill_count: 0
    .wavefront_size: 64
